# GEMM loop: load segments at s_setprio 1, MFMA segments at 0, mid-segment priority flips removed
# speedup vs baseline: 1.0325x; 1.0067x over previous
.LBB0_176:
	s_mov_b32 m0, s55
	s_nop 0
	global_load_lds_dwordx4 v194, s[100:101]
	s_mov_b32 m0, s67
	s_nop 0
	global_load_lds_dwordx4 v196, s[100:101]
	v_add_u32_e32 v130, 0x10000, v243
	v_add_u32_e32 v142, 0x14000, v243
	ds_read_b128 v[146:149], v130
	ds_read_b128 v[150:153], v130 offset:1024
	ds_read_b128 v[154:157], v130 offset:2048
	ds_read_b128 v[158:161], v130 offset:3072
	ds_read_b128 v[130:133], v142
	ds_read_b128 v[134:137], v142 offset:1024
	ds_read_b128 v[138:141], v142 offset:2048
	ds_read_b128 v[142:145], v142 offset:3072
	v_lshl_add_u64 v[246:247], v[234:235], 0, s[80:81]
	s_add_i32 m0, s8, 0xc000
	s_waitcnt lgkmcnt(0)
	ds_read_b128 v[174:177], v244
	ds_read_b128 v[190:193], v244 offset:1024
	ds_read_b128 v[170:173], v244 offset:2048
	ds_read_b128 v[186:189], v244 offset:3072
	ds_read_b128 v[166:169], v244 offset:4096
	ds_read_b128 v[182:185], v244 offset:5120
	ds_read_b128 v[162:165], v244 offset:6144
	ds_read_b128 v[178:181], v244 offset:7168
	global_load_lds_dwordx4 v[246:247], off
	v_lshl_add_u64 v[246:247], v[236:237], 0, s[80:81]
	s_add_i32 m0, s8, 0xe000
	s_nop 0
	global_load_lds_dwordx4 v[246:247], off
	s_waitcnt vmcnt(8)
	s_waitcnt lgkmcnt(0)
	s_barrier
	s_setprio 0
	s_waitcnt lgkmcnt(0)
	v_mfma_f32_16x16x32_bf16 v[118:121], v[146:149], v[174:177], v[118:121]
	v_mfma_f32_16x16x32_bf16 v[126:129], v[154:157], v[174:177], v[126:129]
	v_mfma_f32_16x16x32_bf16 v[102:105], v[146:149], v[170:173], v[102:105]
	v_mfma_f32_16x16x32_bf16 v[110:113], v[154:157], v[170:173], v[110:113]
	v_mfma_f32_16x16x32_bf16 v[86:89], v[146:149], v[166:169], v[86:89]
	v_mfma_f32_16x16x32_bf16 v[94:97], v[154:157], v[166:169], v[94:97]
	v_mfma_f32_16x16x32_bf16 v[70:73], v[146:149], v[162:165], v[70:73]
	v_mfma_f32_16x16x32_bf16 v[78:81], v[154:157], v[162:165], v[78:81]
	v_mfma_f32_16x16x32_bf16 v[118:121], v[150:153], v[190:193], v[118:121]
	v_mfma_f32_16x16x32_bf16 v[126:129], v[158:161], v[190:193], v[126:129]
	v_mfma_f32_16x16x32_bf16 v[102:105], v[150:153], v[186:189], v[102:105]
	v_mfma_f32_16x16x32_bf16 v[110:113], v[158:161], v[186:189], v[110:113]
	v_mfma_f32_16x16x32_bf16 v[86:89], v[150:153], v[182:185], v[86:89]
	v_mfma_f32_16x16x32_bf16 v[94:97], v[158:161], v[182:185], v[94:97]
	v_mfma_f32_16x16x32_bf16 v[70:73], v[150:153], v[178:181], v[70:73]
	v_mfma_f32_16x16x32_bf16 v[78:81], v[158:161], v[178:181], v[78:81]
	v_mfma_f32_16x16x32_bf16 v[122:125], v[130:133], v[174:177], v[122:125]
	v_mfma_f32_16x16x32_bf16 v[114:117], v[138:141], v[174:177], v[114:117]
	v_mfma_f32_16x16x32_bf16 v[106:109], v[130:133], v[170:173], v[106:109]
	v_mfma_f32_16x16x32_bf16 v[98:101], v[138:141], v[170:173], v[98:101]
	v_mfma_f32_16x16x32_bf16 v[90:93], v[130:133], v[166:169], v[90:93]
	v_mfma_f32_16x16x32_bf16 v[82:85], v[138:141], v[166:169], v[82:85]
	v_mfma_f32_16x16x32_bf16 v[74:77], v[130:133], v[162:165], v[74:77]
	v_mfma_f32_16x16x32_bf16 v[66:69], v[138:141], v[162:165], v[66:69]
	v_mfma_f32_16x16x32_bf16 v[122:125], v[134:137], v[190:193], v[122:125]
	v_mfma_f32_16x16x32_bf16 v[114:117], v[142:145], v[190:193], v[114:117]
	v_mfma_f32_16x16x32_bf16 v[106:109], v[134:137], v[186:189], v[106:109]
	v_mfma_f32_16x16x32_bf16 v[98:101], v[142:145], v[186:189], v[98:101]
	v_mfma_f32_16x16x32_bf16 v[90:93], v[134:137], v[182:185], v[90:93]
	v_mfma_f32_16x16x32_bf16 v[82:85], v[142:145], v[182:185], v[82:85]
	v_mfma_f32_16x16x32_bf16 v[74:77], v[134:137], v[178:181], v[74:77]
	v_mfma_f32_16x16x32_bf16 v[66:69], v[142:145], v[178:181], v[66:69]
	s_setprio 1
	s_barrier
	v_cndmask_b32_e64 v246, 0, 1, s[50:51]
	v_cmp_ne_u32_e64 s[48:49], 1, v246
	s_andn2_b64 vcc, exec, s[50:51]
	s_cbranch_vccnz .LBB0_178
	ds_read_b128 v[174:177], v244 offset:16384
	ds_read_b128 v[190:193], v244 offset:17408
	ds_read_b128 v[170:173], v244 offset:18432
	ds_read_b128 v[186:189], v244 offset:19456
	ds_read_b128 v[166:169], v244 offset:20480
	ds_read_b128 v[182:185], v244 offset:21504
	ds_read_b128 v[162:165], v244 offset:22528
	ds_read_b128 v[178:181], v244 offset:23552
.LBB0_178:
	s_add_u32 s82, s0, s80
	s_addc_u32 s83, s1, s81
	s_add_u32 s84, s82, 0x460000
	s_addc_u32 s85, s83, 0
	s_cmp_eq_u32 s80, 0x41a0000
	s_cselect_b64 s[86:87], -1, 0
	s_and_b64 s[82:83], s[86:87], exec
	s_cselect_b32 s83, s71, s97
	s_cselect_b32 s82, s73, s79
	s_mov_b32 m0, s9
	s_cselect_b32 s85, s22, s85
	s_cselect_b32 s84, s69, s84
	s_add_u32 vcc_lo, s82, 0x4000
	global_load_lds_dwordx4 v194, s[82:83]
	s_mov_b32 m0, s10
	s_addc_u32 vcc_hi, s83, 0
	global_load_lds_dwordx4 v196, s[82:83]
	s_mov_b32 m0, s11
	s_nop 0
	global_load_lds_dwordx4 v194, vcc
	v_lshl_add_u64 v[246:247], vcc, 0, v[196:197]
	s_mov_b32 m0, s12
	s_and_b64 vcc, exec, s[48:49]
	global_load_lds_dwordx4 v[246:247], off
	s_mov_b64 s[98:99], s[84:85]
	s_waitcnt vmcnt(6)
	s_waitcnt lgkmcnt(0)
	s_barrier
	s_cbranch_vccnz .LBB0_180
	s_setprio 0
	s_waitcnt lgkmcnt(0)
	v_mfma_f32_16x16x32_bf16 v[54:57], v[146:149], v[174:177], v[54:57]
	v_mfma_f32_16x16x32_bf16 v[62:65], v[154:157], v[174:177], v[62:65]
	v_mfma_f32_16x16x32_bf16 v[38:41], v[146:149], v[170:173], v[38:41]
	v_mfma_f32_16x16x32_bf16 v[46:49], v[154:157], v[170:173], v[46:49]
	v_mfma_f32_16x16x32_bf16 v[22:25], v[146:149], v[166:169], v[22:25]
	v_mfma_f32_16x16x32_bf16 v[30:33], v[154:157], v[166:169], v[30:33]
	v_mfma_f32_16x16x32_bf16 v[10:13], v[146:149], v[162:165], v[10:13]
	v_mfma_f32_16x16x32_bf16 v[14:17], v[154:157], v[162:165], v[14:17]
	v_mfma_f32_16x16x32_bf16 v[54:57], v[150:153], v[190:193], v[54:57]
	v_mfma_f32_16x16x32_bf16 v[62:65], v[158:161], v[190:193], v[62:65]
	v_mfma_f32_16x16x32_bf16 v[38:41], v[150:153], v[186:189], v[38:41]
	v_mfma_f32_16x16x32_bf16 v[46:49], v[158:161], v[186:189], v[46:49]
	v_mfma_f32_16x16x32_bf16 v[22:25], v[150:153], v[182:185], v[22:25]
	v_mfma_f32_16x16x32_bf16 v[30:33], v[158:161], v[182:185], v[30:33]
	v_mfma_f32_16x16x32_bf16 v[10:13], v[150:153], v[178:181], v[10:13]
	v_mfma_f32_16x16x32_bf16 v[14:17], v[158:161], v[178:181], v[14:17]
	v_mfma_f32_16x16x32_bf16 v[58:61], v[130:133], v[174:177], v[58:61]
	v_mfma_f32_16x16x32_bf16 v[50:53], v[138:141], v[174:177], v[50:53]
	v_mfma_f32_16x16x32_bf16 v[42:45], v[130:133], v[170:173], v[42:45]
	v_mfma_f32_16x16x32_bf16 v[34:37], v[138:141], v[170:173], v[34:37]
	v_mfma_f32_16x16x32_bf16 v[26:29], v[130:133], v[166:169], v[26:29]
	v_mfma_f32_16x16x32_bf16 v[18:21], v[138:141], v[166:169], v[18:21]
	v_mfma_f32_16x16x32_bf16 v[6:9], v[130:133], v[162:165], v[6:9]
	v_mfma_f32_16x16x32_bf16 v[2:5], v[138:141], v[162:165], v[2:5]
	v_mfma_f32_16x16x32_bf16 v[58:61], v[134:137], v[190:193], v[58:61]
	v_mfma_f32_16x16x32_bf16 v[50:53], v[142:145], v[190:193], v[50:53]
	v_mfma_f32_16x16x32_bf16 v[42:45], v[134:137], v[186:189], v[42:45]
	v_mfma_f32_16x16x32_bf16 v[34:37], v[142:145], v[186:189], v[34:37]
	v_mfma_f32_16x16x32_bf16 v[26:29], v[134:137], v[182:185], v[26:29]
	v_mfma_f32_16x16x32_bf16 v[18:21], v[142:145], v[182:185], v[18:21]
	v_mfma_f32_16x16x32_bf16 v[6:9], v[134:137], v[178:181], v[6:9]
	v_mfma_f32_16x16x32_bf16 v[2:5], v[142:145], v[178:181], v[2:5]
	s_setprio 1
.LBB0_180:
	s_and_b64 vcc, s[46:47], s[86:87]
	v_cndmask_b32_e64 v131, v233, 0, vcc
	v_cndmask_b32_e32 v130, v232, v198, vcc
	v_lshl_add_u64 v[246:247], s[84:85], 0, v[130:131]
	s_barrier
	s_mov_b32 m0, s8
	s_nop 0
	global_load_lds_dwordx4 v194, s[98:99]
	s_mov_b32 m0, s13
	s_nop 0
	global_load_lds_dwordx4 v196, s[98:99]
	v_add_u32_e32 v130, 0x18000, v243
	v_add_u32_e32 v142, 0x1c000, v243
	ds_read_b128 v[146:149], v130
	ds_read_b128 v[150:153], v130 offset:1024
	ds_read_b128 v[154:157], v130 offset:2048
	ds_read_b128 v[158:161], v130 offset:3072
	ds_read_b128 v[130:133], v142
	ds_read_b128 v[134:137], v142 offset:1024
	ds_read_b128 v[138:141], v142 offset:2048
	ds_read_b128 v[142:145], v142 offset:3072
	s_mov_b32 m0, s14
	v_lshl_add_u64 v[248:249], v[246:247], 0, v[194:195]
	s_waitcnt lgkmcnt(0)
	ds_read_b128 v[174:177], v244 offset:32768
	ds_read_b128 v[190:193], v244 offset:33792
	ds_read_b128 v[170:173], v244 offset:34816
	ds_read_b128 v[186:189], v244 offset:35840
	ds_read_b128 v[166:169], v244 offset:36864
	ds_read_b128 v[182:185], v244 offset:37888
	ds_read_b128 v[162:165], v244 offset:38912
	ds_read_b128 v[178:181], v244 offset:39936
	global_load_lds_dwordx4 v[248:249], off
	v_lshl_add_u64 v[246:247], v[246:247], 0, v[196:197]
	s_mov_b32 m0, s15
	s_nop 0
	global_load_lds_dwordx4 v[246:247], off
	s_waitcnt vmcnt(8)
	s_waitcnt lgkmcnt(0)
	s_barrier
	s_setprio 0
	s_waitcnt lgkmcnt(0)
	v_mfma_f32_16x16x32_bf16 v[118:121], v[146:149], v[174:177], v[118:121]
	v_mfma_f32_16x16x32_bf16 v[126:129], v[154:157], v[174:177], v[126:129]
	v_mfma_f32_16x16x32_bf16 v[102:105], v[146:149], v[170:173], v[102:105]
	v_mfma_f32_16x16x32_bf16 v[110:113], v[154:157], v[170:173], v[110:113]
	v_mfma_f32_16x16x32_bf16 v[86:89], v[146:149], v[166:169], v[86:89]
	v_mfma_f32_16x16x32_bf16 v[94:97], v[154:157], v[166:169], v[94:97]
	v_mfma_f32_16x16x32_bf16 v[70:73], v[146:149], v[162:165], v[70:73]
	v_mfma_f32_16x16x32_bf16 v[78:81], v[154:157], v[162:165], v[78:81]
	v_mfma_f32_16x16x32_bf16 v[118:121], v[150:153], v[190:193], v[118:121]
	v_mfma_f32_16x16x32_bf16 v[126:129], v[158:161], v[190:193], v[126:129]
	v_mfma_f32_16x16x32_bf16 v[102:105], v[150:153], v[186:189], v[102:105]
	v_mfma_f32_16x16x32_bf16 v[110:113], v[158:161], v[186:189], v[110:113]
	v_mfma_f32_16x16x32_bf16 v[86:89], v[150:153], v[182:185], v[86:89]
	v_mfma_f32_16x16x32_bf16 v[94:97], v[158:161], v[182:185], v[94:97]
	v_mfma_f32_16x16x32_bf16 v[70:73], v[150:153], v[178:181], v[70:73]
	v_mfma_f32_16x16x32_bf16 v[78:81], v[158:161], v[178:181], v[78:81]
	v_mfma_f32_16x16x32_bf16 v[122:125], v[130:133], v[174:177], v[122:125]
	v_mfma_f32_16x16x32_bf16 v[114:117], v[138:141], v[174:177], v[114:117]
	v_mfma_f32_16x16x32_bf16 v[106:109], v[130:133], v[170:173], v[106:109]
	v_mfma_f32_16x16x32_bf16 v[98:101], v[138:141], v[170:173], v[98:101]
	v_mfma_f32_16x16x32_bf16 v[90:93], v[130:133], v[166:169], v[90:93]
	v_mfma_f32_16x16x32_bf16 v[82:85], v[138:141], v[166:169], v[82:85]
	v_mfma_f32_16x16x32_bf16 v[74:77], v[130:133], v[162:165], v[74:77]
	v_mfma_f32_16x16x32_bf16 v[66:69], v[138:141], v[162:165], v[66:69]
	v_mfma_f32_16x16x32_bf16 v[122:125], v[134:137], v[190:193], v[122:125]
	v_mfma_f32_16x16x32_bf16 v[114:117], v[142:145], v[190:193], v[114:117]
	v_mfma_f32_16x16x32_bf16 v[106:109], v[134:137], v[186:189], v[106:109]
	v_mfma_f32_16x16x32_bf16 v[98:101], v[142:145], v[186:189], v[98:101]
	v_mfma_f32_16x16x32_bf16 v[90:93], v[134:137], v[182:185], v[90:93]
	v_mfma_f32_16x16x32_bf16 v[82:85], v[142:145], v[182:185], v[82:85]
	v_mfma_f32_16x16x32_bf16 v[74:77], v[134:137], v[178:181], v[74:77]
	v_mfma_f32_16x16x32_bf16 v[66:69], v[142:145], v[178:181], v[66:69]
	s_setprio 1
	s_barrier
	s_and_b64 vcc, exec, s[48:49]
	s_cbranch_vccnz .LBB0_182
	ds_read_b128 v[174:177], v244 offset:49152
	ds_read_b128 v[190:193], v244 offset:50176
	ds_read_b128 v[170:173], v244 offset:51200
	ds_read_b128 v[186:189], v244 offset:52224
	ds_read_b128 v[166:169], v244 offset:53248
	ds_read_b128 v[182:185], v244 offset:54272
	ds_read_b128 v[162:165], v244 offset:55296
	ds_read_b128 v[178:181], v244 offset:56320
.LBB0_182:
	s_add_u32 s86, s82, 0x120000
	s_addc_u32 s87, s83, 0
	s_add_u32 s84, s84, 0x230000
	s_addc_u32 s85, s85, 0
	s_mov_b32 m0, s17
	s_add_u32 s82, s82, 0x124000
	global_load_lds_dwordx4 v194, s[86:87]
	s_mov_b32 m0, s54
	s_addc_u32 s83, s83, 0
	global_load_lds_dwordx4 v196, s[86:87]
	s_mov_b32 m0, s89
	s_and_b64 vcc, exec, s[48:49]
	global_load_lds_dwordx4 v194, s[82:83]
	s_mov_b32 m0, s90
	s_nop 0
	global_load_lds_dwordx4 v196, s[82:83]
	s_mov_b64 s[100:101], s[84:85]
	s_waitcnt vmcnt(6)
	s_waitcnt lgkmcnt(0)
	s_barrier
	s_cbranch_vccnz .LBB0_175
	s_setprio 0
	s_waitcnt lgkmcnt(0)
	v_mfma_f32_16x16x32_bf16 v[54:57], v[146:149], v[174:177], v[54:57]
	v_mfma_f32_16x16x32_bf16 v[62:65], v[154:157], v[174:177], v[62:65]
	v_mfma_f32_16x16x32_bf16 v[38:41], v[146:149], v[170:173], v[38:41]
	v_mfma_f32_16x16x32_bf16 v[46:49], v[154:157], v[170:173], v[46:49]
	v_mfma_f32_16x16x32_bf16 v[22:25], v[146:149], v[166:169], v[22:25]
	v_mfma_f32_16x16x32_bf16 v[30:33], v[154:157], v[166:169], v[30:33]
	v_mfma_f32_16x16x32_bf16 v[10:13], v[146:149], v[162:165], v[10:13]
	v_mfma_f32_16x16x32_bf16 v[14:17], v[154:157], v[162:165], v[14:17]
	v_mfma_f32_16x16x32_bf16 v[54:57], v[150:153], v[190:193], v[54:57]
	v_mfma_f32_16x16x32_bf16 v[62:65], v[158:161], v[190:193], v[62:65]
	v_mfma_f32_16x16x32_bf16 v[38:41], v[150:153], v[186:189], v[38:41]
	v_mfma_f32_16x16x32_bf16 v[46:49], v[158:161], v[186:189], v[46:49]
	v_mfma_f32_16x16x32_bf16 v[22:25], v[150:153], v[182:185], v[22:25]
	v_mfma_f32_16x16x32_bf16 v[30:33], v[158:161], v[182:185], v[30:33]
	v_mfma_f32_16x16x32_bf16 v[10:13], v[150:153], v[178:181], v[10:13]
	v_mfma_f32_16x16x32_bf16 v[14:17], v[158:161], v[178:181], v[14:17]
	v_mfma_f32_16x16x32_bf16 v[58:61], v[130:133], v[174:177], v[58:61]
	v_mfma_f32_16x16x32_bf16 v[50:53], v[138:141], v[174:177], v[50:53]
	v_mfma_f32_16x16x32_bf16 v[42:45], v[130:133], v[170:173], v[42:45]
	v_mfma_f32_16x16x32_bf16 v[34:37], v[138:141], v[170:173], v[34:37]
	v_mfma_f32_16x16x32_bf16 v[26:29], v[130:133], v[166:169], v[26:29]
	v_mfma_f32_16x16x32_bf16 v[18:21], v[138:141], v[166:169], v[18:21]
	v_mfma_f32_16x16x32_bf16 v[6:9], v[130:133], v[162:165], v[6:9]
	v_mfma_f32_16x16x32_bf16 v[2:5], v[138:141], v[162:165], v[2:5]
	v_mfma_f32_16x16x32_bf16 v[58:61], v[134:137], v[190:193], v[58:61]
	v_mfma_f32_16x16x32_bf16 v[50:53], v[142:145], v[190:193], v[50:53]
	v_mfma_f32_16x16x32_bf16 v[42:45], v[134:137], v[186:189], v[42:45]
	v_mfma_f32_16x16x32_bf16 v[34:37], v[142:145], v[186:189], v[34:37]
	v_mfma_f32_16x16x32_bf16 v[26:29], v[134:137], v[182:185], v[26:29]
	v_mfma_f32_16x16x32_bf16 v[18:21], v[142:145], v[182:185], v[18:21]
	v_mfma_f32_16x16x32_bf16 v[6:9], v[134:137], v[178:181], v[6:9]
	v_mfma_f32_16x16x32_bf16 v[2:5], v[142:145], v[178:181], v[2:5]
	s_setprio 1
	s_branch .LBB0_175

.LBB0_559:
	s_mov_b32 m0, s55
	s_nop 0
	global_load_lds_dwordx4 v194, s[100:101]
	s_mov_b32 m0, s67
	s_nop 0
	global_load_lds_dwordx4 v196, s[100:101]
	ds_read_b128 v[146:149], v227
	ds_read_b128 v[150:153], v227 offset:1024
	ds_read_b128 v[154:157], v227 offset:2048
	ds_read_b128 v[158:161], v227 offset:3072
	ds_read_b128 v[130:133], v228
	ds_read_b128 v[134:137], v228 offset:1024
	ds_read_b128 v[138:141], v228 offset:2048
	ds_read_b128 v[142:145], v228 offset:3072
	v_lshl_add_u64 v[234:235], v[216:217], 0, s[58:59]
	s_add_i32 m0, s8, 0xc000
	s_waitcnt lgkmcnt(0)
	ds_read_b128 v[174:177], v229
	ds_read_b128 v[190:193], v229 offset:1024
	ds_read_b128 v[170:173], v229 offset:2048
	ds_read_b128 v[186:189], v229 offset:3072
	ds_read_b128 v[166:169], v229 offset:4096
	ds_read_b128 v[182:185], v229 offset:5120
	ds_read_b128 v[162:165], v229 offset:6144
	ds_read_b128 v[178:181], v229 offset:7168
	global_load_lds_dwordx4 v[234:235], off
	v_lshl_add_u64 v[234:235], v[218:219], 0, s[58:59]
	s_add_i32 m0, s8, 0xe000
	s_nop 0
	global_load_lds_dwordx4 v[234:235], off
	s_waitcnt vmcnt(8)
	s_waitcnt lgkmcnt(0)
	s_barrier
	s_setprio 0
	s_waitcnt lgkmcnt(0)
	v_mfma_f32_16x16x32_bf16 v[126:129], v[146:149], v[174:177], v[126:129]
	v_mfma_f32_16x16x32_bf16 v[122:125], v[154:157], v[174:177], v[122:125]
	v_mfma_f32_16x16x32_bf16 v[110:113], v[146:149], v[170:173], v[110:113]
	v_mfma_f32_16x16x32_bf16 v[106:109], v[154:157], v[170:173], v[106:109]
	v_mfma_f32_16x16x32_bf16 v[94:97], v[146:149], v[166:169], v[94:97]
	v_mfma_f32_16x16x32_bf16 v[90:93], v[154:157], v[166:169], v[90:93]
	v_mfma_f32_16x16x32_bf16 v[78:81], v[146:149], v[162:165], v[78:81]
	v_mfma_f32_16x16x32_bf16 v[74:77], v[154:157], v[162:165], v[74:77]
	v_mfma_f32_16x16x32_bf16 v[126:129], v[150:153], v[190:193], v[126:129]
	v_mfma_f32_16x16x32_bf16 v[122:125], v[158:161], v[190:193], v[122:125]
	v_mfma_f32_16x16x32_bf16 v[110:113], v[150:153], v[186:189], v[110:113]
	v_mfma_f32_16x16x32_bf16 v[106:109], v[158:161], v[186:189], v[106:109]
	v_mfma_f32_16x16x32_bf16 v[94:97], v[150:153], v[182:185], v[94:97]
	v_mfma_f32_16x16x32_bf16 v[90:93], v[158:161], v[182:185], v[90:93]
	v_mfma_f32_16x16x32_bf16 v[78:81], v[150:153], v[178:181], v[78:81]
	v_mfma_f32_16x16x32_bf16 v[74:77], v[158:161], v[178:181], v[74:77]
	v_mfma_f32_16x16x32_bf16 v[118:121], v[130:133], v[174:177], v[118:121]
	v_mfma_f32_16x16x32_bf16 v[114:117], v[138:141], v[174:177], v[114:117]
	v_mfma_f32_16x16x32_bf16 v[102:105], v[130:133], v[170:173], v[102:105]
	v_mfma_f32_16x16x32_bf16 v[98:101], v[138:141], v[170:173], v[98:101]
	v_mfma_f32_16x16x32_bf16 v[86:89], v[130:133], v[166:169], v[86:89]
	v_mfma_f32_16x16x32_bf16 v[82:85], v[138:141], v[166:169], v[82:85]
	v_mfma_f32_16x16x32_bf16 v[70:73], v[130:133], v[162:165], v[70:73]
	v_mfma_f32_16x16x32_bf16 v[66:69], v[138:141], v[162:165], v[66:69]
	v_mfma_f32_16x16x32_bf16 v[118:121], v[134:137], v[190:193], v[118:121]
	v_mfma_f32_16x16x32_bf16 v[114:117], v[142:145], v[190:193], v[114:117]
	v_mfma_f32_16x16x32_bf16 v[102:105], v[134:137], v[186:189], v[102:105]
	v_mfma_f32_16x16x32_bf16 v[98:101], v[142:145], v[186:189], v[98:101]
	v_mfma_f32_16x16x32_bf16 v[86:89], v[134:137], v[182:185], v[86:89]
	v_mfma_f32_16x16x32_bf16 v[82:85], v[142:145], v[182:185], v[82:85]
	v_mfma_f32_16x16x32_bf16 v[70:73], v[134:137], v[178:181], v[70:73]
	v_mfma_f32_16x16x32_bf16 v[66:69], v[142:145], v[178:181], v[66:69]
	s_setprio 1
	s_barrier
	v_cmp_ne_u32_e64 s[42:43], 1, v233
	s_andn2_b64 vcc, exec, s[44:45]
	s_cbranch_vccnz .LBB0_561
	ds_read_b128 v[174:177], v229 offset:16384
	ds_read_b128 v[190:193], v229 offset:17408
	ds_read_b128 v[170:173], v229 offset:18432
	ds_read_b128 v[186:189], v229 offset:19456
	ds_read_b128 v[166:169], v229 offset:20480
	ds_read_b128 v[182:185], v229 offset:21504
	ds_read_b128 v[162:165], v229 offset:22528
	ds_read_b128 v[178:181], v229 offset:23552
.LBB0_561:
	s_add_u32 s60, s56, s58
	s_addc_u32 s61, s57, s59
	s_add_u32 s62, s60, 0x440000
	s_addc_u32 s63, s61, 0
	s_cmp_eq_u32 s58, 0x3fc0000
	s_cselect_b64 s[68:69], -1, 0
	s_and_b64 s[60:61], s[68:69], exec
	s_cselect_b32 s61, s37, s72
	s_cselect_b32 s60, s47, s53
	s_mov_b32 m0, s9
	s_cselect_b32 s63, s1, s63
	s_cselect_b32 s62, s24, s62
	s_add_u32 s74, s60, 0x4000
	global_load_lds_dwordx4 v194, s[60:61]
	s_mov_b32 m0, s10
	s_addc_u32 s75, s61, 0
	global_load_lds_dwordx4 v196, s[60:61]
	s_mov_b32 m0, s11
	s_and_b64 vcc, exec, s[42:43]
	global_load_lds_dwordx4 v194, s[74:75]
	s_mov_b32 m0, s12
	s_nop 0
	global_load_lds_dwordx4 v196, s[74:75]
	s_mov_b64 s[98:99], s[62:63]
	s_waitcnt vmcnt(6)
	s_waitcnt lgkmcnt(0)
	s_barrier
	s_cbranch_vccnz .LBB0_563
	s_setprio 0
	s_waitcnt lgkmcnt(0)
	v_mfma_f32_16x16x32_bf16 v[62:65], v[146:149], v[174:177], v[62:65]
	v_mfma_f32_16x16x32_bf16 v[58:61], v[154:157], v[174:177], v[58:61]
	v_mfma_f32_16x16x32_bf16 v[46:49], v[146:149], v[170:173], v[46:49]
	v_mfma_f32_16x16x32_bf16 v[42:45], v[154:157], v[170:173], v[42:45]
	v_mfma_f32_16x16x32_bf16 v[30:33], v[146:149], v[166:169], v[30:33]
	v_mfma_f32_16x16x32_bf16 v[26:29], v[154:157], v[166:169], v[26:29]
	v_mfma_f32_16x16x32_bf16 v[14:17], v[146:149], v[162:165], v[14:17]
	v_mfma_f32_16x16x32_bf16 v[10:13], v[154:157], v[162:165], v[10:13]
	v_mfma_f32_16x16x32_bf16 v[62:65], v[150:153], v[190:193], v[62:65]
	v_mfma_f32_16x16x32_bf16 v[58:61], v[158:161], v[190:193], v[58:61]
	v_mfma_f32_16x16x32_bf16 v[46:49], v[150:153], v[186:189], v[46:49]
	v_mfma_f32_16x16x32_bf16 v[42:45], v[158:161], v[186:189], v[42:45]
	v_mfma_f32_16x16x32_bf16 v[30:33], v[150:153], v[182:185], v[30:33]
	v_mfma_f32_16x16x32_bf16 v[26:29], v[158:161], v[182:185], v[26:29]
	v_mfma_f32_16x16x32_bf16 v[14:17], v[150:153], v[178:181], v[14:17]
	v_mfma_f32_16x16x32_bf16 v[10:13], v[158:161], v[178:181], v[10:13]
	v_mfma_f32_16x16x32_bf16 v[54:57], v[130:133], v[174:177], v[54:57]
	v_mfma_f32_16x16x32_bf16 v[50:53], v[138:141], v[174:177], v[50:53]
	v_mfma_f32_16x16x32_bf16 v[38:41], v[130:133], v[170:173], v[38:41]
	v_mfma_f32_16x16x32_bf16 v[34:37], v[138:141], v[170:173], v[34:37]
	v_mfma_f32_16x16x32_bf16 v[22:25], v[130:133], v[166:169], v[22:25]
	v_mfma_f32_16x16x32_bf16 v[18:21], v[138:141], v[166:169], v[18:21]
	v_mfma_f32_16x16x32_bf16 v[6:9], v[130:133], v[162:165], v[6:9]
	v_mfma_f32_16x16x32_bf16 v[2:5], v[138:141], v[162:165], v[2:5]
	v_mfma_f32_16x16x32_bf16 v[54:57], v[134:137], v[190:193], v[54:57]
	v_mfma_f32_16x16x32_bf16 v[50:53], v[142:145], v[190:193], v[50:53]
	v_mfma_f32_16x16x32_bf16 v[38:41], v[134:137], v[186:189], v[38:41]
	v_mfma_f32_16x16x32_bf16 v[34:37], v[142:145], v[186:189], v[34:37]
	v_mfma_f32_16x16x32_bf16 v[22:25], v[134:137], v[182:185], v[22:25]
	v_mfma_f32_16x16x32_bf16 v[18:21], v[142:145], v[182:185], v[18:21]
	v_mfma_f32_16x16x32_bf16 v[6:9], v[134:137], v[178:181], v[6:9]
	v_mfma_f32_16x16x32_bf16 v[2:5], v[142:145], v[178:181], v[2:5]
	s_setprio 1
.LBB0_563:
	s_and_b64 vcc, s[40:41], s[68:69]
	v_cndmask_b32_e64 v131, v215, 0, vcc
	v_cndmask_b32_e32 v130, v214, v198, vcc
	v_lshl_add_u64 v[234:235], s[62:63], 0, v[130:131]
	s_barrier
	s_mov_b32 m0, s8
	s_nop 0
	global_load_lds_dwordx4 v194, s[98:99]
	s_mov_b32 m0, s13
	s_nop 0
	global_load_lds_dwordx4 v196, s[98:99]
	v_add_u32_e32 v130, 0x18000, v226
	v_add_u32_e32 v142, 0x1c000, v226
	ds_read_b128 v[146:149], v130
	ds_read_b128 v[150:153], v130 offset:1024
	ds_read_b128 v[154:157], v130 offset:2048
	ds_read_b128 v[158:161], v130 offset:3072
	ds_read_b128 v[130:133], v142
	ds_read_b128 v[134:137], v142 offset:1024
	ds_read_b128 v[138:141], v142 offset:2048
	ds_read_b128 v[142:145], v142 offset:3072
	s_mov_b32 m0, s14
	v_lshl_add_u64 v[236:237], v[234:235], 0, v[194:195]
	s_waitcnt lgkmcnt(0)
	ds_read_b128 v[174:177], v229 offset:32768
	ds_read_b128 v[190:193], v229 offset:33792
	ds_read_b128 v[170:173], v229 offset:34816
	ds_read_b128 v[186:189], v229 offset:35840
	ds_read_b128 v[166:169], v229 offset:36864
	ds_read_b128 v[182:185], v229 offset:37888
	ds_read_b128 v[162:165], v229 offset:38912
	ds_read_b128 v[178:181], v229 offset:39936
	global_load_lds_dwordx4 v[236:237], off
	v_lshl_add_u64 v[234:235], v[234:235], 0, v[196:197]
	s_mov_b32 m0, s15
	s_nop 0
	global_load_lds_dwordx4 v[234:235], off
	s_waitcnt vmcnt(8)
	s_waitcnt lgkmcnt(0)
	s_barrier
	s_setprio 0
	s_waitcnt lgkmcnt(0)
	v_mfma_f32_16x16x32_bf16 v[126:129], v[146:149], v[174:177], v[126:129]
	v_mfma_f32_16x16x32_bf16 v[122:125], v[154:157], v[174:177], v[122:125]
	v_mfma_f32_16x16x32_bf16 v[110:113], v[146:149], v[170:173], v[110:113]
	v_mfma_f32_16x16x32_bf16 v[106:109], v[154:157], v[170:173], v[106:109]
	v_mfma_f32_16x16x32_bf16 v[94:97], v[146:149], v[166:169], v[94:97]
	v_mfma_f32_16x16x32_bf16 v[90:93], v[154:157], v[166:169], v[90:93]
	v_mfma_f32_16x16x32_bf16 v[78:81], v[146:149], v[162:165], v[78:81]
	v_mfma_f32_16x16x32_bf16 v[74:77], v[154:157], v[162:165], v[74:77]
	v_mfma_f32_16x16x32_bf16 v[126:129], v[150:153], v[190:193], v[126:129]
	v_mfma_f32_16x16x32_bf16 v[122:125], v[158:161], v[190:193], v[122:125]
	v_mfma_f32_16x16x32_bf16 v[110:113], v[150:153], v[186:189], v[110:113]
	v_mfma_f32_16x16x32_bf16 v[106:109], v[158:161], v[186:189], v[106:109]
	v_mfma_f32_16x16x32_bf16 v[94:97], v[150:153], v[182:185], v[94:97]
	v_mfma_f32_16x16x32_bf16 v[90:93], v[158:161], v[182:185], v[90:93]
	v_mfma_f32_16x16x32_bf16 v[78:81], v[150:153], v[178:181], v[78:81]
	v_mfma_f32_16x16x32_bf16 v[74:77], v[158:161], v[178:181], v[74:77]
	v_mfma_f32_16x16x32_bf16 v[118:121], v[130:133], v[174:177], v[118:121]
	v_mfma_f32_16x16x32_bf16 v[114:117], v[138:141], v[174:177], v[114:117]
	v_mfma_f32_16x16x32_bf16 v[102:105], v[130:133], v[170:173], v[102:105]
	v_mfma_f32_16x16x32_bf16 v[98:101], v[138:141], v[170:173], v[98:101]
	v_mfma_f32_16x16x32_bf16 v[86:89], v[130:133], v[166:169], v[86:89]
	v_mfma_f32_16x16x32_bf16 v[82:85], v[138:141], v[166:169], v[82:85]
	v_mfma_f32_16x16x32_bf16 v[70:73], v[130:133], v[162:165], v[70:73]
	v_mfma_f32_16x16x32_bf16 v[66:69], v[138:141], v[162:165], v[66:69]
	v_mfma_f32_16x16x32_bf16 v[118:121], v[134:137], v[190:193], v[118:121]
	v_mfma_f32_16x16x32_bf16 v[114:117], v[142:145], v[190:193], v[114:117]
	v_mfma_f32_16x16x32_bf16 v[102:105], v[134:137], v[186:189], v[102:105]
	v_mfma_f32_16x16x32_bf16 v[98:101], v[142:145], v[186:189], v[98:101]
	v_mfma_f32_16x16x32_bf16 v[86:89], v[134:137], v[182:185], v[86:89]
	v_mfma_f32_16x16x32_bf16 v[82:85], v[142:145], v[182:185], v[82:85]
	v_mfma_f32_16x16x32_bf16 v[70:73], v[134:137], v[178:181], v[70:73]
	v_mfma_f32_16x16x32_bf16 v[66:69], v[142:145], v[178:181], v[66:69]
	s_setprio 1
	s_barrier
	s_and_b64 vcc, exec, s[42:43]
	s_cbranch_vccnz .LBB0_565
	ds_read_b128 v[174:177], v229 offset:49152
	ds_read_b128 v[190:193], v229 offset:50176
	ds_read_b128 v[170:173], v229 offset:51200
	ds_read_b128 v[186:189], v229 offset:52224
	ds_read_b128 v[166:169], v229 offset:53248
	ds_read_b128 v[182:185], v229 offset:54272
	ds_read_b128 v[162:165], v229 offset:55296
	ds_read_b128 v[178:181], v229 offset:56320
.LBB0_565:
	s_add_u32 s68, s60, 0x40000
	s_addc_u32 s69, s61, 0
	s_add_u32 s62, s62, 0x220000
	s_addc_u32 s63, s63, 0
	s_mov_b32 m0, s17
	s_add_u32 s60, s60, 0x44000
	global_load_lds_dwordx4 v194, s[68:69]
	s_mov_b32 m0, s54
	s_addc_u32 s61, s61, 0
	global_load_lds_dwordx4 v196, s[68:69]
	s_mov_b32 m0, s70
	s_and_b64 vcc, exec, s[42:43]
	global_load_lds_dwordx4 v194, s[60:61]
	s_mov_b32 m0, s71
	s_nop 0
	global_load_lds_dwordx4 v196, s[60:61]
	s_mov_b64 s[100:101], s[62:63]
	s_waitcnt vmcnt(6)
	s_waitcnt lgkmcnt(0)
	s_barrier
	s_cbranch_vccnz .LBB0_558
	s_setprio 0
	s_waitcnt lgkmcnt(0)
	v_mfma_f32_16x16x32_bf16 v[62:65], v[146:149], v[174:177], v[62:65]
	v_mfma_f32_16x16x32_bf16 v[58:61], v[154:157], v[174:177], v[58:61]
	v_mfma_f32_16x16x32_bf16 v[46:49], v[146:149], v[170:173], v[46:49]
	v_mfma_f32_16x16x32_bf16 v[42:45], v[154:157], v[170:173], v[42:45]
	v_mfma_f32_16x16x32_bf16 v[30:33], v[146:149], v[166:169], v[30:33]
	v_mfma_f32_16x16x32_bf16 v[26:29], v[154:157], v[166:169], v[26:29]
	v_mfma_f32_16x16x32_bf16 v[14:17], v[146:149], v[162:165], v[14:17]
	v_mfma_f32_16x16x32_bf16 v[10:13], v[154:157], v[162:165], v[10:13]
	v_mfma_f32_16x16x32_bf16 v[62:65], v[150:153], v[190:193], v[62:65]
	v_mfma_f32_16x16x32_bf16 v[58:61], v[158:161], v[190:193], v[58:61]
	v_mfma_f32_16x16x32_bf16 v[46:49], v[150:153], v[186:189], v[46:49]
	v_mfma_f32_16x16x32_bf16 v[42:45], v[158:161], v[186:189], v[42:45]
	v_mfma_f32_16x16x32_bf16 v[30:33], v[150:153], v[182:185], v[30:33]
	v_mfma_f32_16x16x32_bf16 v[26:29], v[158:161], v[182:185], v[26:29]
	v_mfma_f32_16x16x32_bf16 v[14:17], v[150:153], v[178:181], v[14:17]
	v_mfma_f32_16x16x32_bf16 v[10:13], v[158:161], v[178:181], v[10:13]
	v_mfma_f32_16x16x32_bf16 v[54:57], v[130:133], v[174:177], v[54:57]
	v_mfma_f32_16x16x32_bf16 v[50:53], v[138:141], v[174:177], v[50:53]
	v_mfma_f32_16x16x32_bf16 v[38:41], v[130:133], v[170:173], v[38:41]
	v_mfma_f32_16x16x32_bf16 v[34:37], v[138:141], v[170:173], v[34:37]
	v_mfma_f32_16x16x32_bf16 v[22:25], v[130:133], v[166:169], v[22:25]
	v_mfma_f32_16x16x32_bf16 v[18:21], v[138:141], v[166:169], v[18:21]
	v_mfma_f32_16x16x32_bf16 v[6:9], v[130:133], v[162:165], v[6:9]
	v_mfma_f32_16x16x32_bf16 v[2:5], v[138:141], v[162:165], v[2:5]
	v_mfma_f32_16x16x32_bf16 v[54:57], v[134:137], v[190:193], v[54:57]
	v_mfma_f32_16x16x32_bf16 v[50:53], v[142:145], v[190:193], v[50:53]
	v_mfma_f32_16x16x32_bf16 v[38:41], v[134:137], v[186:189], v[38:41]
	v_mfma_f32_16x16x32_bf16 v[34:37], v[142:145], v[186:189], v[34:37]
	v_mfma_f32_16x16x32_bf16 v[22:25], v[134:137], v[182:185], v[22:25]
	v_mfma_f32_16x16x32_bf16 v[18:21], v[142:145], v[182:185], v[18:21]
	v_mfma_f32_16x16x32_bf16 v[6:9], v[134:137], v[178:181], v[6:9]
	v_mfma_f32_16x16x32_bf16 v[2:5], v[142:145], v[178:181], v[2:5]
	s_setprio 1
	s_branch .LBB0_558

.LBB0_761:
	s_mov_b32 m0, s14
	s_nop 0
	global_load_lds_dwordx4 v194, s[100:101]
	s_mov_b32 m0, s15
	s_nop 0
	global_load_lds_dwordx4 v196, s[100:101]
	ds_read_b128 v[130:133], v237
	ds_read_b128 v[134:137], v237 offset:1024
	ds_read_b128 v[138:141], v237 offset:2048
	ds_read_b128 v[142:145], v237 offset:3072
	ds_read_b128 v[146:149], v238
	ds_read_b128 v[150:153], v238 offset:1024
	ds_read_b128 v[154:157], v238 offset:2048
	ds_read_b128 v[158:161], v238 offset:3072
	s_add_u32 s48, s0, 0x21c000
	s_addc_u32 s49, s1, 0
	s_cmp_eq_u32 s67, 28
	s_cselect_b32 s42, s55, s62
	s_cselect_b32 s43, s29, s63
	s_cselect_b32 s52, s45, s48
	s_cselect_b32 s53, s31, s49
	s_add_u32 s50, s42, 0xe0000
	s_addc_u32 s51, s43, 0
	s_add_u32 s48, s52, 0x220000
	s_addc_u32 s49, s53, 0
	v_lshl_add_u64 v[208:209], s[0:1], 0, v[202:203]
	s_add_i32 m0, s9, 0xc000
	ds_read_b128 v[162:165], v239
	ds_read_b128 v[166:169], v239 offset:1024
	ds_read_b128 v[170:173], v239 offset:2048
	ds_read_b128 v[174:177], v239 offset:3072
	ds_read_b128 v[178:181], v239 offset:4096
	ds_read_b128 v[182:185], v239 offset:5120
	ds_read_b128 v[186:189], v239 offset:6144
	ds_read_b128 v[190:193], v239 offset:7168
	global_load_lds_dwordx4 v[208:209], off
	v_lshl_add_u64 v[208:209], s[0:1], 0, v[200:201]
	s_add_i32 m0, s9, 0xe000
	s_nop 0
	global_load_lds_dwordx4 v[208:209], off
	s_waitcnt vmcnt(8)
	s_waitcnt lgkmcnt(0)
	s_barrier
	s_setprio 0
	s_waitcnt lgkmcnt(0)
	v_mfma_f32_16x16x32_bf16 v[126:129], v[130:133], v[162:165], v[126:129]
	v_mfma_f32_16x16x32_bf16 v[122:125], v[138:141], v[162:165], v[122:125]
	v_mfma_f32_16x16x32_bf16 v[118:121], v[130:133], v[170:173], v[118:121]
	v_mfma_f32_16x16x32_bf16 v[114:117], v[138:141], v[170:173], v[114:117]
	v_mfma_f32_16x16x32_bf16 v[110:113], v[130:133], v[178:181], v[110:113]
	v_mfma_f32_16x16x32_bf16 v[106:109], v[138:141], v[178:181], v[106:109]
	v_mfma_f32_16x16x32_bf16 v[102:105], v[130:133], v[186:189], v[102:105]
	v_mfma_f32_16x16x32_bf16 v[98:101], v[138:141], v[186:189], v[98:101]
	v_mfma_f32_16x16x32_bf16 v[126:129], v[134:137], v[166:169], v[126:129]
	v_mfma_f32_16x16x32_bf16 v[122:125], v[142:145], v[166:169], v[122:125]
	v_mfma_f32_16x16x32_bf16 v[118:121], v[134:137], v[174:177], v[118:121]
	v_mfma_f32_16x16x32_bf16 v[114:117], v[142:145], v[174:177], v[114:117]
	v_mfma_f32_16x16x32_bf16 v[110:113], v[134:137], v[182:185], v[110:113]
	v_mfma_f32_16x16x32_bf16 v[106:109], v[142:145], v[182:185], v[106:109]
	v_mfma_f32_16x16x32_bf16 v[102:105], v[134:137], v[190:193], v[102:105]
	v_mfma_f32_16x16x32_bf16 v[98:101], v[142:145], v[190:193], v[98:101]
	v_mfma_f32_16x16x32_bf16 v[62:65], v[146:149], v[162:165], v[62:65]
	s_add_u32 s60, s52, 0x4000
	s_addc_u32 s61, s53, 0
	v_mfma_f32_16x16x32_bf16 v[58:61], v[154:157], v[162:165], v[58:61]
	v_mfma_f32_16x16x32_bf16 v[54:57], v[146:149], v[170:173], v[54:57]
	v_mfma_f32_16x16x32_bf16 v[50:53], v[154:157], v[170:173], v[50:53]
	v_mfma_f32_16x16x32_bf16 v[46:49], v[146:149], v[178:181], v[46:49]
	v_mfma_f32_16x16x32_bf16 v[42:45], v[154:157], v[178:181], v[42:45]
	v_mfma_f32_16x16x32_bf16 v[38:41], v[146:149], v[186:189], v[38:41]
	v_mfma_f32_16x16x32_bf16 v[34:37], v[154:157], v[186:189], v[34:37]
	v_mfma_f32_16x16x32_bf16 v[62:65], v[150:153], v[166:169], v[62:65]
	v_mfma_f32_16x16x32_bf16 v[58:61], v[158:161], v[166:169], v[58:61]
	v_mfma_f32_16x16x32_bf16 v[54:57], v[150:153], v[174:177], v[54:57]
	v_mfma_f32_16x16x32_bf16 v[50:53], v[158:161], v[174:177], v[50:53]
	v_mfma_f32_16x16x32_bf16 v[46:49], v[150:153], v[182:185], v[46:49]
	v_mfma_f32_16x16x32_bf16 v[42:45], v[158:161], v[182:185], v[42:45]
	v_mfma_f32_16x16x32_bf16 v[38:41], v[150:153], v[190:193], v[38:41]
	v_mfma_f32_16x16x32_bf16 v[34:37], v[158:161], v[190:193], v[34:37]
	s_setprio 1
	s_barrier
	s_add_i32 s68, s16, s8
	s_mov_b32 m0, s68
	ds_read_b128 v[162:165], v239 offset:16384
	ds_read_b128 v[166:169], v239 offset:17408
	ds_read_b128 v[170:173], v239 offset:18432
	ds_read_b128 v[174:177], v239 offset:19456
	ds_read_b128 v[178:181], v239 offset:20480
	ds_read_b128 v[182:185], v239 offset:21504
	ds_read_b128 v[186:189], v239 offset:22528
	ds_read_b128 v[190:193], v239 offset:23552
	global_load_lds_dwordx4 v194, s[42:43]
	s_add_i32 m0, s68, 0x2000
	s_add_u32 s68, s42, 0x4000
	s_addc_u32 s69, s43, 0
	s_add_i32 s70, s17, s8
	global_load_lds_dwordx4 v196, s[42:43]
	s_mov_b32 m0, s70
	s_nop 0
	global_load_lds_dwordx4 v194, s[68:69]
	s_add_i32 m0, s70, 0x2000
	s_nop 0
	global_load_lds_dwordx4 v196, s[68:69]
	s_mov_b64 s[98:99], s[52:53]
	s_waitcnt vmcnt(6)
	s_waitcnt lgkmcnt(0)
	s_barrier
	s_setprio 0
	s_waitcnt lgkmcnt(0)
	v_mfma_f32_16x16x32_bf16 v[94:97], v[130:133], v[162:165], v[94:97]
	v_mfma_f32_16x16x32_bf16 v[90:93], v[138:141], v[162:165], v[90:93]
	v_mfma_f32_16x16x32_bf16 v[86:89], v[130:133], v[170:173], v[86:89]
	v_mfma_f32_16x16x32_bf16 v[82:85], v[138:141], v[170:173], v[82:85]
	v_mfma_f32_16x16x32_bf16 v[78:81], v[130:133], v[178:181], v[78:81]
	v_mfma_f32_16x16x32_bf16 v[74:77], v[138:141], v[178:181], v[74:77]
	v_mfma_f32_16x16x32_bf16 v[70:73], v[130:133], v[186:189], v[70:73]
	v_mfma_f32_16x16x32_bf16 v[66:69], v[138:141], v[186:189], v[66:69]
	v_mfma_f32_16x16x32_bf16 v[94:97], v[134:137], v[166:169], v[94:97]
	v_mfma_f32_16x16x32_bf16 v[90:93], v[142:145], v[166:169], v[90:93]
	v_mfma_f32_16x16x32_bf16 v[86:89], v[134:137], v[174:177], v[86:89]
	v_mfma_f32_16x16x32_bf16 v[82:85], v[142:145], v[174:177], v[82:85]
	v_mfma_f32_16x16x32_bf16 v[78:81], v[134:137], v[182:185], v[78:81]
	v_mfma_f32_16x16x32_bf16 v[74:77], v[142:145], v[182:185], v[74:77]
	v_mfma_f32_16x16x32_bf16 v[70:73], v[134:137], v[190:193], v[70:73]
	v_mfma_f32_16x16x32_bf16 v[66:69], v[142:145], v[190:193], v[66:69]
	v_mfma_f32_16x16x32_bf16 v[30:33], v[146:149], v[162:165], v[30:33]
	v_mfma_f32_16x16x32_bf16 v[26:29], v[154:157], v[162:165], v[26:29]
	v_mfma_f32_16x16x32_bf16 v[22:25], v[146:149], v[170:173], v[22:25]
	v_mfma_f32_16x16x32_bf16 v[18:21], v[154:157], v[170:173], v[18:21]
	v_mfma_f32_16x16x32_bf16 v[14:17], v[146:149], v[178:181], v[14:17]
	v_mfma_f32_16x16x32_bf16 v[10:13], v[154:157], v[178:181], v[10:13]
	v_mfma_f32_16x16x32_bf16 v[6:9], v[146:149], v[186:189], v[6:9]
	v_mfma_f32_16x16x32_bf16 v[2:5], v[154:157], v[186:189], v[2:5]
	v_mfma_f32_16x16x32_bf16 v[30:33], v[150:153], v[166:169], v[30:33]
	v_mfma_f32_16x16x32_bf16 v[26:29], v[158:161], v[166:169], v[26:29]
	v_mfma_f32_16x16x32_bf16 v[22:25], v[150:153], v[174:177], v[22:25]
	v_mfma_f32_16x16x32_bf16 v[18:21], v[158:161], v[174:177], v[18:21]
	v_mfma_f32_16x16x32_bf16 v[14:17], v[150:153], v[182:185], v[14:17]
	v_mfma_f32_16x16x32_bf16 v[10:13], v[158:161], v[182:185], v[10:13]
	v_mfma_f32_16x16x32_bf16 v[6:9], v[150:153], v[190:193], v[6:9]
	v_mfma_f32_16x16x32_bf16 v[2:5], v[158:161], v[190:193], v[2:5]
	s_setprio 1
	s_barrier
	s_mov_b32 m0, s9
	s_nop 0
	global_load_lds_dwordx4 v194, s[98:99]
	s_mov_b32 m0, s10
	s_nop 0
	global_load_lds_dwordx4 v196, s[98:99]
	s_add_i32 s52, 0, 0x18000
	s_add_i32 s53, 0, 0x1c000
	v_add_u32_e32 v142, s52, v228
	v_add_u32_e32 v158, s53, v228
	ds_read_b128 v[130:133], v142
	ds_read_b128 v[134:137], v142 offset:1024
	ds_read_b128 v[138:141], v142 offset:2048
	ds_read_b128 v[142:145], v142 offset:3072
	ds_read_b128 v[146:149], v158
	ds_read_b128 v[150:153], v158 offset:1024
	ds_read_b128 v[154:157], v158 offset:2048
	ds_read_b128 v[158:161], v158 offset:3072
	s_mov_b32 m0, s11
	ds_read_b128 v[162:165], v239 offset:32768
	ds_read_b128 v[166:169], v239 offset:33792
	ds_read_b128 v[170:173], v239 offset:34816
	ds_read_b128 v[174:177], v239 offset:35840
	ds_read_b128 v[178:181], v239 offset:36864
	ds_read_b128 v[182:185], v239 offset:37888
	ds_read_b128 v[186:189], v239 offset:38912
	ds_read_b128 v[190:193], v239 offset:39936
	global_load_lds_dwordx4 v194, s[60:61]
	s_mov_b32 m0, s12
	s_nop 0
	global_load_lds_dwordx4 v196, s[60:61]
	s_waitcnt vmcnt(8)
	s_waitcnt lgkmcnt(0)
	s_barrier
	s_setprio 0
	s_waitcnt lgkmcnt(0)
	v_mfma_f32_16x16x32_bf16 v[126:129], v[130:133], v[162:165], v[126:129]
	v_mfma_f32_16x16x32_bf16 v[122:125], v[138:141], v[162:165], v[122:125]
	v_mfma_f32_16x16x32_bf16 v[118:121], v[130:133], v[170:173], v[118:121]
	v_mfma_f32_16x16x32_bf16 v[114:117], v[138:141], v[170:173], v[114:117]
	v_mfma_f32_16x16x32_bf16 v[110:113], v[130:133], v[178:181], v[110:113]
	v_mfma_f32_16x16x32_bf16 v[106:109], v[138:141], v[178:181], v[106:109]
	v_mfma_f32_16x16x32_bf16 v[102:105], v[130:133], v[186:189], v[102:105]
	v_mfma_f32_16x16x32_bf16 v[98:101], v[138:141], v[186:189], v[98:101]
	v_mfma_f32_16x16x32_bf16 v[126:129], v[134:137], v[166:169], v[126:129]
	v_mfma_f32_16x16x32_bf16 v[122:125], v[142:145], v[166:169], v[122:125]
	v_mfma_f32_16x16x32_bf16 v[118:121], v[134:137], v[174:177], v[118:121]
	v_mfma_f32_16x16x32_bf16 v[114:117], v[142:145], v[174:177], v[114:117]
	v_mfma_f32_16x16x32_bf16 v[110:113], v[134:137], v[182:185], v[110:113]
	v_mfma_f32_16x16x32_bf16 v[106:109], v[142:145], v[182:185], v[106:109]
	v_mfma_f32_16x16x32_bf16 v[102:105], v[134:137], v[190:193], v[102:105]
	v_mfma_f32_16x16x32_bf16 v[98:101], v[142:145], v[190:193], v[98:101]
	v_mfma_f32_16x16x32_bf16 v[62:65], v[146:149], v[162:165], v[62:65]
	v_mfma_f32_16x16x32_bf16 v[58:61], v[154:157], v[162:165], v[58:61]
	v_mfma_f32_16x16x32_bf16 v[54:57], v[146:149], v[170:173], v[54:57]
	v_mfma_f32_16x16x32_bf16 v[50:53], v[154:157], v[170:173], v[50:53]
	v_mfma_f32_16x16x32_bf16 v[46:49], v[146:149], v[178:181], v[46:49]
	v_mfma_f32_16x16x32_bf16 v[42:45], v[154:157], v[178:181], v[42:45]
	v_mfma_f32_16x16x32_bf16 v[38:41], v[146:149], v[186:189], v[38:41]
	v_mfma_f32_16x16x32_bf16 v[34:37], v[154:157], v[186:189], v[34:37]
	v_mfma_f32_16x16x32_bf16 v[62:65], v[150:153], v[166:169], v[62:65]
	v_mfma_f32_16x16x32_bf16 v[58:61], v[158:161], v[166:169], v[58:61]
	v_mfma_f32_16x16x32_bf16 v[54:57], v[150:153], v[174:177], v[54:57]
	v_mfma_f32_16x16x32_bf16 v[50:53], v[158:161], v[174:177], v[50:53]
	v_mfma_f32_16x16x32_bf16 v[46:49], v[150:153], v[182:185], v[46:49]
	v_mfma_f32_16x16x32_bf16 v[42:45], v[158:161], v[182:185], v[42:45]
	v_mfma_f32_16x16x32_bf16 v[38:41], v[150:153], v[190:193], v[38:41]
	v_mfma_f32_16x16x32_bf16 v[34:37], v[158:161], v[190:193], v[34:37]
	s_setprio 1
	s_barrier
	s_add_i32 s52, s52, s8
	s_mov_b32 m0, s52
	ds_read_b128 v[162:165], v239 offset:49152
	ds_read_b128 v[166:169], v239 offset:50176
	ds_read_b128 v[170:173], v239 offset:51200
	ds_read_b128 v[174:177], v239 offset:52224
	ds_read_b128 v[178:181], v239 offset:53248
	ds_read_b128 v[182:185], v239 offset:54272
	ds_read_b128 v[186:189], v239 offset:55296
	ds_read_b128 v[190:193], v239 offset:56320
	global_load_lds_dwordx4 v194, s[50:51]
	s_add_i32 m0, s52, 0x2000
	s_add_u32 s42, s42, 0xe4000
	v_lshl_add_u64 v[208:209], s[50:51], 0, v[196:197]
	s_addc_u32 s43, s43, 0
	s_add_i32 s50, s53, s8
	global_load_lds_dwordx4 v[208:209], off
	s_mov_b32 m0, s50
	s_nop 0
	global_load_lds_dwordx4 v194, s[42:43]
	s_add_i32 m0, s50, 0x2000
	s_nop 0
	global_load_lds_dwordx4 v196, s[42:43]
	s_mov_b64 s[100:101], s[48:49]
	s_waitcnt vmcnt(6)
	s_waitcnt lgkmcnt(0)
	s_barrier
	s_setprio 0
	s_waitcnt lgkmcnt(0)
	v_mfma_f32_16x16x32_bf16 v[94:97], v[130:133], v[162:165], v[94:97]
	v_mfma_f32_16x16x32_bf16 v[90:93], v[138:141], v[162:165], v[90:93]
	v_mfma_f32_16x16x32_bf16 v[86:89], v[130:133], v[170:173], v[86:89]
	v_mfma_f32_16x16x32_bf16 v[82:85], v[138:141], v[170:173], v[82:85]
	v_mfma_f32_16x16x32_bf16 v[78:81], v[130:133], v[178:181], v[78:81]
	v_mfma_f32_16x16x32_bf16 v[74:77], v[138:141], v[178:181], v[74:77]
	v_mfma_f32_16x16x32_bf16 v[70:73], v[130:133], v[186:189], v[70:73]
	v_mfma_f32_16x16x32_bf16 v[66:69], v[138:141], v[186:189], v[66:69]
	v_mfma_f32_16x16x32_bf16 v[94:97], v[134:137], v[166:169], v[94:97]
	v_mfma_f32_16x16x32_bf16 v[90:93], v[142:145], v[166:169], v[90:93]
	v_mfma_f32_16x16x32_bf16 v[86:89], v[134:137], v[174:177], v[86:89]
	v_mfma_f32_16x16x32_bf16 v[82:85], v[142:145], v[174:177], v[82:85]
	v_mfma_f32_16x16x32_bf16 v[78:81], v[134:137], v[182:185], v[78:81]
	v_mfma_f32_16x16x32_bf16 v[74:77], v[142:145], v[182:185], v[74:77]
	v_mfma_f32_16x16x32_bf16 v[70:73], v[134:137], v[190:193], v[70:73]
	v_mfma_f32_16x16x32_bf16 v[66:69], v[142:145], v[190:193], v[66:69]
	v_mfma_f32_16x16x32_bf16 v[30:33], v[146:149], v[162:165], v[30:33]
	v_mfma_f32_16x16x32_bf16 v[26:29], v[154:157], v[162:165], v[26:29]
	v_mfma_f32_16x16x32_bf16 v[22:25], v[146:149], v[170:173], v[22:25]
	v_mfma_f32_16x16x32_bf16 v[18:21], v[154:157], v[170:173], v[18:21]
	v_mfma_f32_16x16x32_bf16 v[14:17], v[146:149], v[178:181], v[14:17]
	v_mfma_f32_16x16x32_bf16 v[10:13], v[154:157], v[178:181], v[10:13]
	v_mfma_f32_16x16x32_bf16 v[6:9], v[146:149], v[186:189], v[6:9]
	v_mfma_f32_16x16x32_bf16 v[2:5], v[154:157], v[186:189], v[2:5]
	v_mfma_f32_16x16x32_bf16 v[30:33], v[150:153], v[166:169], v[30:33]
	v_mfma_f32_16x16x32_bf16 v[26:29], v[158:161], v[166:169], v[26:29]
	v_mfma_f32_16x16x32_bf16 v[22:25], v[150:153], v[174:177], v[22:25]
	v_mfma_f32_16x16x32_bf16 v[18:21], v[158:161], v[174:177], v[18:21]
	v_mfma_f32_16x16x32_bf16 v[14:17], v[150:153], v[182:185], v[14:17]
	v_mfma_f32_16x16x32_bf16 v[10:13], v[158:161], v[182:185], v[10:13]
	v_mfma_f32_16x16x32_bf16 v[6:9], v[150:153], v[190:193], v[6:9]
	v_mfma_f32_16x16x32_bf16 v[2:5], v[158:161], v[190:193], v[2:5]
	s_setprio 1
	s_barrier
	s_add_i32 s67, s67, 2
	s_add_u32 s62, s62, 0x1c0000
	s_addc_u32 s63, s63, 0
	s_add_u32 s0, s0, 0x440000
	s_addc_u32 s1, s1, 0
	s_cmp_gt_u32 s67, 29
	s_cbranch_scc0 .LBB0_761
	s_and_b64 vcc, exec, s[26:27]
	s_cbranch_vccz .LBB0_764
	s_barrier

.LBB0_903:
	s_mov_b32 m0, s23
	s_nop 0
	global_load_lds_dwordx4 v194, s[100:101]
	s_mov_b32 m0, s31
	s_nop 0
	global_load_lds_dwordx4 v196, s[100:101]
	ds_read_b128 v[146:149], v225
	ds_read_b128 v[150:153], v225 offset:1024
	ds_read_b128 v[154:157], v225 offset:2048
	ds_read_b128 v[158:161], v225 offset:3072
	ds_read_b128 v[130:133], v227
	ds_read_b128 v[134:137], v227 offset:1024
	ds_read_b128 v[138:141], v227 offset:2048
	ds_read_b128 v[142:145], v227 offset:3072
	v_lshl_add_u64 v[234:235], v[210:211], 0, s[62:63]
	s_add_i32 m0, s8, 0xc000
	s_waitcnt lgkmcnt(0)
	ds_read_b128 v[174:177], v228
	ds_read_b128 v[190:193], v228 offset:1024
	ds_read_b128 v[170:173], v228 offset:2048
	ds_read_b128 v[186:189], v228 offset:3072
	ds_read_b128 v[166:169], v228 offset:4096
	ds_read_b128 v[182:185], v228 offset:5120
	ds_read_b128 v[162:165], v228 offset:6144
	ds_read_b128 v[178:181], v228 offset:7168
	global_load_lds_dwordx4 v[234:235], off
	v_lshl_add_u64 v[234:235], v[212:213], 0, s[62:63]
	s_add_i32 m0, s8, 0xe000
	s_nop 0
	global_load_lds_dwordx4 v[234:235], off
	s_waitcnt vmcnt(8)
	s_waitcnt lgkmcnt(0)
	s_barrier
	s_setprio 0
	s_waitcnt lgkmcnt(0)
	v_mfma_f32_16x16x32_bf16 v[126:129], v[146:149], v[174:177], v[126:129]
	v_mfma_f32_16x16x32_bf16 v[122:125], v[154:157], v[174:177], v[122:125]
	v_mfma_f32_16x16x32_bf16 v[118:121], v[146:149], v[170:173], v[118:121]
	v_mfma_f32_16x16x32_bf16 v[114:117], v[154:157], v[170:173], v[114:117]
	v_mfma_f32_16x16x32_bf16 v[110:113], v[146:149], v[166:169], v[110:113]
	v_mfma_f32_16x16x32_bf16 v[106:109], v[154:157], v[166:169], v[106:109]
	v_mfma_f32_16x16x32_bf16 v[102:105], v[146:149], v[162:165], v[102:105]
	v_mfma_f32_16x16x32_bf16 v[98:101], v[154:157], v[162:165], v[98:101]
	v_mfma_f32_16x16x32_bf16 v[126:129], v[150:153], v[190:193], v[126:129]
	v_mfma_f32_16x16x32_bf16 v[122:125], v[158:161], v[190:193], v[122:125]
	v_mfma_f32_16x16x32_bf16 v[118:121], v[150:153], v[186:189], v[118:121]
	v_mfma_f32_16x16x32_bf16 v[114:117], v[158:161], v[186:189], v[114:117]
	v_mfma_f32_16x16x32_bf16 v[110:113], v[150:153], v[182:185], v[110:113]
	v_mfma_f32_16x16x32_bf16 v[106:109], v[158:161], v[182:185], v[106:109]
	v_mfma_f32_16x16x32_bf16 v[102:105], v[150:153], v[178:181], v[102:105]
	v_mfma_f32_16x16x32_bf16 v[98:101], v[158:161], v[178:181], v[98:101]
	v_mfma_f32_16x16x32_bf16 v[94:97], v[130:133], v[174:177], v[94:97]
	v_mfma_f32_16x16x32_bf16 v[90:93], v[138:141], v[174:177], v[90:93]
	v_mfma_f32_16x16x32_bf16 v[86:89], v[130:133], v[170:173], v[86:89]
	v_mfma_f32_16x16x32_bf16 v[82:85], v[138:141], v[170:173], v[82:85]
	v_mfma_f32_16x16x32_bf16 v[78:81], v[130:133], v[166:169], v[78:81]
	v_mfma_f32_16x16x32_bf16 v[74:77], v[138:141], v[166:169], v[74:77]
	v_mfma_f32_16x16x32_bf16 v[70:73], v[130:133], v[162:165], v[70:73]
	v_mfma_f32_16x16x32_bf16 v[66:69], v[138:141], v[162:165], v[66:69]
	v_mfma_f32_16x16x32_bf16 v[94:97], v[134:137], v[190:193], v[94:97]
	v_mfma_f32_16x16x32_bf16 v[90:93], v[142:145], v[190:193], v[90:93]
	v_mfma_f32_16x16x32_bf16 v[86:89], v[134:137], v[186:189], v[86:89]
	v_mfma_f32_16x16x32_bf16 v[82:85], v[142:145], v[186:189], v[82:85]
	v_mfma_f32_16x16x32_bf16 v[78:81], v[134:137], v[182:185], v[78:81]
	v_mfma_f32_16x16x32_bf16 v[74:77], v[142:145], v[182:185], v[74:77]
	v_mfma_f32_16x16x32_bf16 v[70:73], v[134:137], v[178:181], v[70:73]
	v_mfma_f32_16x16x32_bf16 v[66:69], v[142:145], v[178:181], v[66:69]
	s_setprio 1
	s_barrier
	v_cmp_ne_u32_e64 s[42:43], 1, v233
	s_andn2_b64 vcc, exec, s[44:45]
	s_cbranch_vccnz .LBB0_905
	ds_read_b128 v[174:177], v228 offset:16384
	ds_read_b128 v[190:193], v228 offset:17408
	ds_read_b128 v[170:173], v228 offset:18432
	ds_read_b128 v[186:189], v228 offset:19456
	ds_read_b128 v[166:169], v228 offset:20480
	ds_read_b128 v[182:185], v228 offset:21504
	ds_read_b128 v[162:165], v228 offset:22528
	ds_read_b128 v[178:181], v228 offset:23552
.LBB0_905:
	s_add_u32 s68, s0, s62
	s_addc_u32 s69, s1, s63
	s_add_u32 s70, s68, 0x440000
	s_addc_u32 s71, s69, 0
	s_cmp_eq_u32 s62, 0x3fc0000
	s_cselect_b64 s[72:73], -1, 0
	s_and_b64 s[68:69], s[72:73], exec
	s_cselect_b32 s69, s37, s77
	s_cselect_b32 s68, s75, s76
	s_mov_b32 m0, s9
	s_cselect_b32 s71, s35, s71
	s_cselect_b32 s70, s74, s70
	s_add_u32 s80, s68, 0x4000
	global_load_lds_dwordx4 v194, s[68:69]
	s_mov_b32 m0, s10
	s_addc_u32 s81, s69, 0
	global_load_lds_dwordx4 v196, s[68:69]
	s_mov_b32 m0, s11
	s_and_b64 vcc, exec, s[42:43]
	global_load_lds_dwordx4 v194, s[80:81]
	s_mov_b32 m0, s12
	s_nop 0
	global_load_lds_dwordx4 v196, s[80:81]
	s_mov_b64 s[98:99], s[70:71]
	s_waitcnt vmcnt(6)
	s_waitcnt lgkmcnt(0)
	s_barrier
	s_cbranch_vccnz .LBB0_907
	s_setprio 0
	s_waitcnt lgkmcnt(0)
	v_mfma_f32_16x16x32_bf16 v[62:65], v[146:149], v[174:177], v[62:65]
	v_mfma_f32_16x16x32_bf16 v[58:61], v[154:157], v[174:177], v[58:61]
	v_mfma_f32_16x16x32_bf16 v[54:57], v[146:149], v[170:173], v[54:57]
	v_mfma_f32_16x16x32_bf16 v[50:53], v[154:157], v[170:173], v[50:53]
	v_mfma_f32_16x16x32_bf16 v[46:49], v[146:149], v[166:169], v[46:49]
	v_mfma_f32_16x16x32_bf16 v[42:45], v[154:157], v[166:169], v[42:45]
	v_mfma_f32_16x16x32_bf16 v[38:41], v[146:149], v[162:165], v[38:41]
	v_mfma_f32_16x16x32_bf16 v[34:37], v[154:157], v[162:165], v[34:37]
	v_mfma_f32_16x16x32_bf16 v[62:65], v[150:153], v[190:193], v[62:65]
	v_mfma_f32_16x16x32_bf16 v[58:61], v[158:161], v[190:193], v[58:61]
	v_mfma_f32_16x16x32_bf16 v[54:57], v[150:153], v[186:189], v[54:57]
	v_mfma_f32_16x16x32_bf16 v[50:53], v[158:161], v[186:189], v[50:53]
	v_mfma_f32_16x16x32_bf16 v[46:49], v[150:153], v[182:185], v[46:49]
	v_mfma_f32_16x16x32_bf16 v[42:45], v[158:161], v[182:185], v[42:45]
	v_mfma_f32_16x16x32_bf16 v[38:41], v[150:153], v[178:181], v[38:41]
	v_mfma_f32_16x16x32_bf16 v[34:37], v[158:161], v[178:181], v[34:37]
	v_mfma_f32_16x16x32_bf16 v[30:33], v[130:133], v[174:177], v[30:33]
	v_mfma_f32_16x16x32_bf16 v[26:29], v[138:141], v[174:177], v[26:29]
	v_mfma_f32_16x16x32_bf16 v[22:25], v[130:133], v[170:173], v[22:25]
	v_mfma_f32_16x16x32_bf16 v[18:21], v[138:141], v[170:173], v[18:21]
	v_mfma_f32_16x16x32_bf16 v[14:17], v[130:133], v[166:169], v[14:17]
	v_mfma_f32_16x16x32_bf16 v[10:13], v[138:141], v[166:169], v[10:13]
	v_mfma_f32_16x16x32_bf16 v[6:9], v[130:133], v[162:165], v[6:9]
	v_mfma_f32_16x16x32_bf16 v[2:5], v[138:141], v[162:165], v[2:5]
	v_mfma_f32_16x16x32_bf16 v[30:33], v[134:137], v[190:193], v[30:33]
	v_mfma_f32_16x16x32_bf16 v[26:29], v[142:145], v[190:193], v[26:29]
	v_mfma_f32_16x16x32_bf16 v[22:25], v[134:137], v[186:189], v[22:25]
	v_mfma_f32_16x16x32_bf16 v[18:21], v[142:145], v[186:189], v[18:21]
	v_mfma_f32_16x16x32_bf16 v[14:17], v[134:137], v[182:185], v[14:17]
	v_mfma_f32_16x16x32_bf16 v[10:13], v[142:145], v[182:185], v[10:13]
	v_mfma_f32_16x16x32_bf16 v[6:9], v[134:137], v[178:181], v[6:9]
	v_mfma_f32_16x16x32_bf16 v[2:5], v[142:145], v[178:181], v[2:5]
	s_setprio 1
.LBB0_907:
	s_and_b64 vcc, s[40:41], s[72:73]
	v_cndmask_b32_e64 v131, v209, 0, vcc
	v_cndmask_b32_e32 v130, v208, v198, vcc
	v_lshl_add_u64 v[234:235], s[70:71], 0, v[130:131]
	s_barrier
	s_mov_b32 m0, s8
	s_nop 0
	global_load_lds_dwordx4 v194, s[98:99]
	s_mov_b32 m0, s13
	s_nop 0
	global_load_lds_dwordx4 v196, s[98:99]
	v_add_u32_e32 v130, 0x18000, v224
	v_add_u32_e32 v142, 0x1c000, v224
	ds_read_b128 v[146:149], v130
	ds_read_b128 v[150:153], v130 offset:1024
	ds_read_b128 v[154:157], v130 offset:2048
	ds_read_b128 v[158:161], v130 offset:3072
	ds_read_b128 v[130:133], v142
	ds_read_b128 v[134:137], v142 offset:1024
	ds_read_b128 v[138:141], v142 offset:2048
	ds_read_b128 v[142:145], v142 offset:3072
	s_mov_b32 m0, s14
	v_lshl_add_u64 v[236:237], v[234:235], 0, v[194:195]
	s_waitcnt lgkmcnt(0)
	ds_read_b128 v[174:177], v228 offset:32768
	ds_read_b128 v[190:193], v228 offset:33792
	ds_read_b128 v[170:173], v228 offset:34816
	ds_read_b128 v[186:189], v228 offset:35840
	ds_read_b128 v[166:169], v228 offset:36864
	ds_read_b128 v[182:185], v228 offset:37888
	ds_read_b128 v[162:165], v228 offset:38912
	ds_read_b128 v[178:181], v228 offset:39936
	global_load_lds_dwordx4 v[236:237], off
	v_lshl_add_u64 v[234:235], v[234:235], 0, v[196:197]
	s_mov_b32 m0, s15
	s_nop 0
	global_load_lds_dwordx4 v[234:235], off
	s_waitcnt vmcnt(8)
	s_waitcnt lgkmcnt(0)
	s_barrier
	s_setprio 0
	s_waitcnt lgkmcnt(0)
	v_mfma_f32_16x16x32_bf16 v[126:129], v[146:149], v[174:177], v[126:129]
	v_mfma_f32_16x16x32_bf16 v[122:125], v[154:157], v[174:177], v[122:125]
	v_mfma_f32_16x16x32_bf16 v[118:121], v[146:149], v[170:173], v[118:121]
	v_mfma_f32_16x16x32_bf16 v[114:117], v[154:157], v[170:173], v[114:117]
	v_mfma_f32_16x16x32_bf16 v[110:113], v[146:149], v[166:169], v[110:113]
	v_mfma_f32_16x16x32_bf16 v[106:109], v[154:157], v[166:169], v[106:109]
	v_mfma_f32_16x16x32_bf16 v[102:105], v[146:149], v[162:165], v[102:105]
	v_mfma_f32_16x16x32_bf16 v[98:101], v[154:157], v[162:165], v[98:101]
	v_mfma_f32_16x16x32_bf16 v[126:129], v[150:153], v[190:193], v[126:129]
	v_mfma_f32_16x16x32_bf16 v[122:125], v[158:161], v[190:193], v[122:125]
	v_mfma_f32_16x16x32_bf16 v[118:121], v[150:153], v[186:189], v[118:121]
	v_mfma_f32_16x16x32_bf16 v[114:117], v[158:161], v[186:189], v[114:117]
	v_mfma_f32_16x16x32_bf16 v[110:113], v[150:153], v[182:185], v[110:113]
	v_mfma_f32_16x16x32_bf16 v[106:109], v[158:161], v[182:185], v[106:109]
	v_mfma_f32_16x16x32_bf16 v[102:105], v[150:153], v[178:181], v[102:105]
	v_mfma_f32_16x16x32_bf16 v[98:101], v[158:161], v[178:181], v[98:101]
	v_mfma_f32_16x16x32_bf16 v[94:97], v[130:133], v[174:177], v[94:97]
	v_mfma_f32_16x16x32_bf16 v[90:93], v[138:141], v[174:177], v[90:93]
	v_mfma_f32_16x16x32_bf16 v[86:89], v[130:133], v[170:173], v[86:89]
	v_mfma_f32_16x16x32_bf16 v[82:85], v[138:141], v[170:173], v[82:85]
	v_mfma_f32_16x16x32_bf16 v[78:81], v[130:133], v[166:169], v[78:81]
	v_mfma_f32_16x16x32_bf16 v[74:77], v[138:141], v[166:169], v[74:77]
	v_mfma_f32_16x16x32_bf16 v[70:73], v[130:133], v[162:165], v[70:73]
	v_mfma_f32_16x16x32_bf16 v[66:69], v[138:141], v[162:165], v[66:69]
	v_mfma_f32_16x16x32_bf16 v[94:97], v[134:137], v[190:193], v[94:97]
	v_mfma_f32_16x16x32_bf16 v[90:93], v[142:145], v[190:193], v[90:93]
	v_mfma_f32_16x16x32_bf16 v[86:89], v[134:137], v[186:189], v[86:89]
	v_mfma_f32_16x16x32_bf16 v[82:85], v[142:145], v[186:189], v[82:85]
	v_mfma_f32_16x16x32_bf16 v[78:81], v[134:137], v[182:185], v[78:81]
	v_mfma_f32_16x16x32_bf16 v[74:77], v[142:145], v[182:185], v[74:77]
	v_mfma_f32_16x16x32_bf16 v[70:73], v[134:137], v[178:181], v[70:73]
	v_mfma_f32_16x16x32_bf16 v[66:69], v[142:145], v[178:181], v[66:69]
	s_setprio 1
	s_barrier
	s_and_b64 vcc, exec, s[42:43]
	s_cbranch_vccnz .LBB0_909
	ds_read_b128 v[174:177], v228 offset:49152
	ds_read_b128 v[190:193], v228 offset:50176
	ds_read_b128 v[170:173], v228 offset:51200
	ds_read_b128 v[186:189], v228 offset:52224
	ds_read_b128 v[166:169], v228 offset:53248
	ds_read_b128 v[182:185], v228 offset:54272
	ds_read_b128 v[162:165], v228 offset:55296
	ds_read_b128 v[178:181], v228 offset:56320
.LBB0_909:
	s_add_u32 s72, s68, 0xe0000
	s_addc_u32 s73, s69, 0
	s_add_u32 s70, s70, 0x220000
	s_addc_u32 s71, s71, 0
	s_mov_b32 m0, s16
	s_add_u32 s68, s68, 0xe4000
	global_load_lds_dwordx4 v194, s[72:73]
	s_mov_b32 m0, s17
	s_addc_u32 s69, s69, 0
	global_load_lds_dwordx4 v196, s[72:73]
	s_mov_b32 m0, s54
	s_and_b64 vcc, exec, s[42:43]
	global_load_lds_dwordx4 v194, s[68:69]
	s_mov_b32 m0, s55
	s_nop 0
	global_load_lds_dwordx4 v196, s[68:69]
	s_mov_b64 s[100:101], s[70:71]
	s_waitcnt vmcnt(6)
	s_waitcnt lgkmcnt(0)
	s_barrier
	s_cbranch_vccnz .LBB0_902
	s_setprio 0
	s_waitcnt lgkmcnt(0)
	v_mfma_f32_16x16x32_bf16 v[62:65], v[146:149], v[174:177], v[62:65]
	v_mfma_f32_16x16x32_bf16 v[58:61], v[154:157], v[174:177], v[58:61]
	v_mfma_f32_16x16x32_bf16 v[54:57], v[146:149], v[170:173], v[54:57]
	v_mfma_f32_16x16x32_bf16 v[50:53], v[154:157], v[170:173], v[50:53]
	v_mfma_f32_16x16x32_bf16 v[46:49], v[146:149], v[166:169], v[46:49]
	v_mfma_f32_16x16x32_bf16 v[42:45], v[154:157], v[166:169], v[42:45]
	v_mfma_f32_16x16x32_bf16 v[38:41], v[146:149], v[162:165], v[38:41]
	v_mfma_f32_16x16x32_bf16 v[34:37], v[154:157], v[162:165], v[34:37]
	v_mfma_f32_16x16x32_bf16 v[62:65], v[150:153], v[190:193], v[62:65]
	v_mfma_f32_16x16x32_bf16 v[58:61], v[158:161], v[190:193], v[58:61]
	v_mfma_f32_16x16x32_bf16 v[54:57], v[150:153], v[186:189], v[54:57]
	v_mfma_f32_16x16x32_bf16 v[50:53], v[158:161], v[186:189], v[50:53]
	v_mfma_f32_16x16x32_bf16 v[46:49], v[150:153], v[182:185], v[46:49]
	v_mfma_f32_16x16x32_bf16 v[42:45], v[158:161], v[182:185], v[42:45]
	v_mfma_f32_16x16x32_bf16 v[38:41], v[150:153], v[178:181], v[38:41]
	v_mfma_f32_16x16x32_bf16 v[34:37], v[158:161], v[178:181], v[34:37]
	v_mfma_f32_16x16x32_bf16 v[30:33], v[130:133], v[174:177], v[30:33]
	v_mfma_f32_16x16x32_bf16 v[26:29], v[138:141], v[174:177], v[26:29]
	v_mfma_f32_16x16x32_bf16 v[22:25], v[130:133], v[170:173], v[22:25]
	v_mfma_f32_16x16x32_bf16 v[18:21], v[138:141], v[170:173], v[18:21]
	v_mfma_f32_16x16x32_bf16 v[14:17], v[130:133], v[166:169], v[14:17]
	v_mfma_f32_16x16x32_bf16 v[10:13], v[138:141], v[166:169], v[10:13]
	v_mfma_f32_16x16x32_bf16 v[6:9], v[130:133], v[162:165], v[6:9]
	v_mfma_f32_16x16x32_bf16 v[2:5], v[138:141], v[162:165], v[2:5]
	v_mfma_f32_16x16x32_bf16 v[30:33], v[134:137], v[190:193], v[30:33]
	v_mfma_f32_16x16x32_bf16 v[26:29], v[142:145], v[190:193], v[26:29]
	v_mfma_f32_16x16x32_bf16 v[22:25], v[134:137], v[186:189], v[22:25]
	v_mfma_f32_16x16x32_bf16 v[18:21], v[142:145], v[186:189], v[18:21]
	v_mfma_f32_16x16x32_bf16 v[14:17], v[134:137], v[182:185], v[14:17]
	v_mfma_f32_16x16x32_bf16 v[10:13], v[142:145], v[182:185], v[10:13]
	v_mfma_f32_16x16x32_bf16 v[6:9], v[134:137], v[178:181], v[6:9]
	v_mfma_f32_16x16x32_bf16 v[2:5], v[142:145], v[178:181], v[2:5]
	s_setprio 1
	s_branch .LBB0_902

.LBB0_1289:
	s_mov_b32 m0, s27
	s_nop 0
	global_load_lds_dwordx4 v194, s[100:101]
	s_mov_b32 m0, s54
	s_nop 0
	global_load_lds_dwordx4 v196, s[100:101]
	v_add_u32_e32 v142, 0x14000, v229
	ds_read_b128 v[146:149], v230
	ds_read_b128 v[150:153], v230 offset:1024
	ds_read_b128 v[154:157], v230 offset:2048
	ds_read_b128 v[158:161], v230 offset:3072
	ds_read_b128 v[130:133], v142
	ds_read_b128 v[134:137], v142 offset:1024
	ds_read_b128 v[138:141], v142 offset:2048
	ds_read_b128 v[142:145], v142 offset:3072
	v_lshl_add_u64 v[234:235], v[222:223], 0, s[48:49]
	s_add_i32 m0, s8, 0xc000
	s_waitcnt lgkmcnt(0)
	ds_read_b128 v[174:177], v231
	ds_read_b128 v[190:193], v231 offset:1024
	ds_read_b128 v[170:173], v231 offset:2048
	ds_read_b128 v[186:189], v231 offset:3072
	ds_read_b128 v[166:169], v231 offset:4096
	ds_read_b128 v[182:185], v231 offset:5120
	ds_read_b128 v[162:165], v231 offset:6144
	ds_read_b128 v[178:181], v231 offset:7168
	global_load_lds_dwordx4 v[234:235], off
	v_lshl_add_u64 v[234:235], v[224:225], 0, s[48:49]
	s_add_i32 m0, s8, 0xe000
	s_nop 0
	global_load_lds_dwordx4 v[234:235], off
	s_waitcnt vmcnt(8)
	s_waitcnt lgkmcnt(0)
	s_barrier
	s_setprio 0
	s_waitcnt lgkmcnt(0)
	v_mfma_f32_16x16x32_bf16 v[126:129], v[146:149], v[174:177], v[126:129]
	v_mfma_f32_16x16x32_bf16 v[122:125], v[154:157], v[174:177], v[122:125]
	v_mfma_f32_16x16x32_bf16 v[118:121], v[146:149], v[170:173], v[118:121]
	v_mfma_f32_16x16x32_bf16 v[110:113], v[154:157], v[170:173], v[110:113]
	v_mfma_f32_16x16x32_bf16 v[102:105], v[146:149], v[166:169], v[102:105]
	v_mfma_f32_16x16x32_bf16 v[94:97], v[154:157], v[166:169], v[94:97]
	v_mfma_f32_16x16x32_bf16 v[86:89], v[146:149], v[162:165], v[86:89]
	v_mfma_f32_16x16x32_bf16 v[78:81], v[154:157], v[162:165], v[78:81]
	v_mfma_f32_16x16x32_bf16 v[126:129], v[150:153], v[190:193], v[126:129]
	v_mfma_f32_16x16x32_bf16 v[122:125], v[158:161], v[190:193], v[122:125]
	v_mfma_f32_16x16x32_bf16 v[118:121], v[150:153], v[186:189], v[118:121]
	v_mfma_f32_16x16x32_bf16 v[110:113], v[158:161], v[186:189], v[110:113]
	v_mfma_f32_16x16x32_bf16 v[102:105], v[150:153], v[182:185], v[102:105]
	v_mfma_f32_16x16x32_bf16 v[94:97], v[158:161], v[182:185], v[94:97]
	v_mfma_f32_16x16x32_bf16 v[86:89], v[150:153], v[178:181], v[86:89]
	v_mfma_f32_16x16x32_bf16 v[78:81], v[158:161], v[178:181], v[78:81]
	v_mfma_f32_16x16x32_bf16 v[114:117], v[130:133], v[174:177], v[114:117]
	v_mfma_f32_16x16x32_bf16 v[106:109], v[138:141], v[174:177], v[106:109]
	v_mfma_f32_16x16x32_bf16 v[98:101], v[130:133], v[170:173], v[98:101]
	v_mfma_f32_16x16x32_bf16 v[90:93], v[138:141], v[170:173], v[90:93]
	v_mfma_f32_16x16x32_bf16 v[82:85], v[130:133], v[166:169], v[82:85]
	v_mfma_f32_16x16x32_bf16 v[74:77], v[138:141], v[166:169], v[74:77]
	v_mfma_f32_16x16x32_bf16 v[70:73], v[130:133], v[162:165], v[70:73]
	v_mfma_f32_16x16x32_bf16 v[66:69], v[138:141], v[162:165], v[66:69]
	v_mfma_f32_16x16x32_bf16 v[114:117], v[134:137], v[190:193], v[114:117]
	v_mfma_f32_16x16x32_bf16 v[106:109], v[142:145], v[190:193], v[106:109]
	v_mfma_f32_16x16x32_bf16 v[98:101], v[134:137], v[186:189], v[98:101]
	v_mfma_f32_16x16x32_bf16 v[90:93], v[142:145], v[186:189], v[90:93]
	v_mfma_f32_16x16x32_bf16 v[82:85], v[134:137], v[182:185], v[82:85]
	v_mfma_f32_16x16x32_bf16 v[74:77], v[142:145], v[182:185], v[74:77]
	v_mfma_f32_16x16x32_bf16 v[70:73], v[134:137], v[178:181], v[70:73]
	v_mfma_f32_16x16x32_bf16 v[66:69], v[142:145], v[178:181], v[66:69]
	s_setprio 1
	s_barrier
	v_cndmask_b32_e64 v233, 0, 1, s[40:41]
	v_cmp_ne_u32_e64 s[42:43], 1, v233
	s_andn2_b64 vcc, exec, s[40:41]
	s_cbranch_vccnz .LBB0_1291
	ds_read_b128 v[174:177], v231 offset:16384
	ds_read_b128 v[190:193], v231 offset:17408
	ds_read_b128 v[170:173], v231 offset:18432
	ds_read_b128 v[186:189], v231 offset:19456
	ds_read_b128 v[166:169], v231 offset:20480
	ds_read_b128 v[182:185], v231 offset:21504
	ds_read_b128 v[162:165], v231 offset:22528
	ds_read_b128 v[178:181], v231 offset:23552
.LBB0_1291:
	s_add_u32 s52, s36, s48
	s_addc_u32 s53, s37, s49
	s_add_u32 s56, s52, 0x440000
	s_addc_u32 s57, s53, 0
	s_cmp_eq_u32 s48, 0x3fc0000
	s_cselect_b64 s[58:59], -1, 0
	s_and_b64 s[52:53], s[58:59], exec
	s_cselect_b32 s53, s31, s63
	s_cselect_b32 s52, s61, s62
	s_mov_b32 m0, s9
	s_cselect_b32 s57, s19, s57
	s_cselect_b32 s56, s29, s56
	s_add_u32 s68, s52, 0x4000
	global_load_lds_dwordx4 v194, s[52:53]
	s_mov_b32 m0, s10
	s_addc_u32 s69, s53, 0
	global_load_lds_dwordx4 v196, s[52:53]
	s_mov_b32 m0, s11
	s_and_b64 vcc, exec, s[42:43]
	global_load_lds_dwordx4 v194, s[68:69]
	s_mov_b32 m0, s12
	s_nop 0
	global_load_lds_dwordx4 v196, s[68:69]
	s_mov_b64 s[98:99], s[56:57]
	s_waitcnt vmcnt(6)
	s_waitcnt lgkmcnt(0)
	s_barrier
	s_cbranch_vccnz .LBB0_1293
	s_setprio 0
	s_waitcnt lgkmcnt(0)
	v_mfma_f32_16x16x32_bf16 v[62:65], v[146:149], v[174:177], v[62:65]
	v_mfma_f32_16x16x32_bf16 v[58:61], v[154:157], v[174:177], v[58:61]
	v_mfma_f32_16x16x32_bf16 v[46:49], v[146:149], v[170:173], v[46:49]
	v_mfma_f32_16x16x32_bf16 v[42:45], v[154:157], v[170:173], v[42:45]
	v_mfma_f32_16x16x32_bf16 v[30:33], v[146:149], v[166:169], v[30:33]
	v_mfma_f32_16x16x32_bf16 v[26:29], v[154:157], v[166:169], v[26:29]
	v_mfma_f32_16x16x32_bf16 v[14:17], v[146:149], v[162:165], v[14:17]
	v_mfma_f32_16x16x32_bf16 v[10:13], v[154:157], v[162:165], v[10:13]
	v_mfma_f32_16x16x32_bf16 v[62:65], v[150:153], v[190:193], v[62:65]
	v_mfma_f32_16x16x32_bf16 v[58:61], v[158:161], v[190:193], v[58:61]
	v_mfma_f32_16x16x32_bf16 v[46:49], v[150:153], v[186:189], v[46:49]
	v_mfma_f32_16x16x32_bf16 v[42:45], v[158:161], v[186:189], v[42:45]
	v_mfma_f32_16x16x32_bf16 v[30:33], v[150:153], v[182:185], v[30:33]
	v_mfma_f32_16x16x32_bf16 v[26:29], v[158:161], v[182:185], v[26:29]
	v_mfma_f32_16x16x32_bf16 v[14:17], v[150:153], v[178:181], v[14:17]
	v_mfma_f32_16x16x32_bf16 v[10:13], v[158:161], v[178:181], v[10:13]
	v_mfma_f32_16x16x32_bf16 v[54:57], v[130:133], v[174:177], v[54:57]
	v_mfma_f32_16x16x32_bf16 v[50:53], v[138:141], v[174:177], v[50:53]
	v_mfma_f32_16x16x32_bf16 v[38:41], v[130:133], v[170:173], v[38:41]
	v_mfma_f32_16x16x32_bf16 v[34:37], v[138:141], v[170:173], v[34:37]
	v_mfma_f32_16x16x32_bf16 v[22:25], v[130:133], v[166:169], v[22:25]
	v_mfma_f32_16x16x32_bf16 v[18:21], v[138:141], v[166:169], v[18:21]
	v_mfma_f32_16x16x32_bf16 v[6:9], v[130:133], v[162:165], v[6:9]
	v_mfma_f32_16x16x32_bf16 v[2:5], v[138:141], v[162:165], v[2:5]
	v_mfma_f32_16x16x32_bf16 v[54:57], v[134:137], v[190:193], v[54:57]
	v_mfma_f32_16x16x32_bf16 v[50:53], v[142:145], v[190:193], v[50:53]
	v_mfma_f32_16x16x32_bf16 v[38:41], v[134:137], v[186:189], v[38:41]
	v_mfma_f32_16x16x32_bf16 v[34:37], v[142:145], v[186:189], v[34:37]
	v_mfma_f32_16x16x32_bf16 v[22:25], v[134:137], v[182:185], v[22:25]
	v_mfma_f32_16x16x32_bf16 v[18:21], v[142:145], v[182:185], v[18:21]
	v_mfma_f32_16x16x32_bf16 v[6:9], v[134:137], v[178:181], v[6:9]
	v_mfma_f32_16x16x32_bf16 v[2:5], v[142:145], v[178:181], v[2:5]
	s_setprio 1
.LBB0_1293:
	s_and_b64 vcc, s[34:35], s[58:59]
	v_cndmask_b32_e64 v131, v221, 0, vcc
	v_cndmask_b32_e32 v130, v220, v198, vcc
	v_lshl_add_u64 v[234:235], s[56:57], 0, v[130:131]
	s_barrier
	s_mov_b32 m0, s8
	s_nop 0
	global_load_lds_dwordx4 v194, s[98:99]
	s_mov_b32 m0, s13
	s_nop 0
	global_load_lds_dwordx4 v196, s[98:99]
	v_add_u32_e32 v130, 0x18000, v229
	v_add_u32_e32 v142, 0x1c000, v229
	ds_read_b128 v[146:149], v130
	ds_read_b128 v[150:153], v130 offset:1024
	ds_read_b128 v[154:157], v130 offset:2048
	ds_read_b128 v[158:161], v130 offset:3072
	ds_read_b128 v[130:133], v142
	ds_read_b128 v[134:137], v142 offset:1024
	ds_read_b128 v[138:141], v142 offset:2048
	ds_read_b128 v[142:145], v142 offset:3072
	s_mov_b32 m0, s14
	v_lshl_add_u64 v[236:237], v[234:235], 0, v[194:195]
	s_waitcnt lgkmcnt(0)
	ds_read_b128 v[174:177], v231 offset:32768
	ds_read_b128 v[190:193], v231 offset:33792
	ds_read_b128 v[170:173], v231 offset:34816
	ds_read_b128 v[186:189], v231 offset:35840
	ds_read_b128 v[166:169], v231 offset:36864
	ds_read_b128 v[182:185], v231 offset:37888
	ds_read_b128 v[162:165], v231 offset:38912
	ds_read_b128 v[178:181], v231 offset:39936
	global_load_lds_dwordx4 v[236:237], off
	v_lshl_add_u64 v[234:235], v[234:235], 0, v[196:197]
	s_mov_b32 m0, s15
	s_nop 0
	global_load_lds_dwordx4 v[234:235], off
	s_waitcnt vmcnt(8)
	s_waitcnt lgkmcnt(0)
	s_barrier
	s_setprio 0
	s_waitcnt lgkmcnt(0)
	v_mfma_f32_16x16x32_bf16 v[126:129], v[146:149], v[174:177], v[126:129]
	v_mfma_f32_16x16x32_bf16 v[122:125], v[154:157], v[174:177], v[122:125]
	v_mfma_f32_16x16x32_bf16 v[118:121], v[146:149], v[170:173], v[118:121]
	v_mfma_f32_16x16x32_bf16 v[110:113], v[154:157], v[170:173], v[110:113]
	v_mfma_f32_16x16x32_bf16 v[102:105], v[146:149], v[166:169], v[102:105]
	v_mfma_f32_16x16x32_bf16 v[94:97], v[154:157], v[166:169], v[94:97]
	v_mfma_f32_16x16x32_bf16 v[86:89], v[146:149], v[162:165], v[86:89]
	v_mfma_f32_16x16x32_bf16 v[78:81], v[154:157], v[162:165], v[78:81]
	v_mfma_f32_16x16x32_bf16 v[126:129], v[150:153], v[190:193], v[126:129]
	v_mfma_f32_16x16x32_bf16 v[122:125], v[158:161], v[190:193], v[122:125]
	v_mfma_f32_16x16x32_bf16 v[118:121], v[150:153], v[186:189], v[118:121]
	v_mfma_f32_16x16x32_bf16 v[110:113], v[158:161], v[186:189], v[110:113]
	v_mfma_f32_16x16x32_bf16 v[102:105], v[150:153], v[182:185], v[102:105]
	v_mfma_f32_16x16x32_bf16 v[94:97], v[158:161], v[182:185], v[94:97]
	v_mfma_f32_16x16x32_bf16 v[86:89], v[150:153], v[178:181], v[86:89]
	v_mfma_f32_16x16x32_bf16 v[78:81], v[158:161], v[178:181], v[78:81]
	v_mfma_f32_16x16x32_bf16 v[114:117], v[130:133], v[174:177], v[114:117]
	v_mfma_f32_16x16x32_bf16 v[106:109], v[138:141], v[174:177], v[106:109]
	v_mfma_f32_16x16x32_bf16 v[98:101], v[130:133], v[170:173], v[98:101]
	v_mfma_f32_16x16x32_bf16 v[90:93], v[138:141], v[170:173], v[90:93]
	v_mfma_f32_16x16x32_bf16 v[82:85], v[130:133], v[166:169], v[82:85]
	v_mfma_f32_16x16x32_bf16 v[74:77], v[138:141], v[166:169], v[74:77]
	v_mfma_f32_16x16x32_bf16 v[70:73], v[130:133], v[162:165], v[70:73]
	v_mfma_f32_16x16x32_bf16 v[66:69], v[138:141], v[162:165], v[66:69]
	v_mfma_f32_16x16x32_bf16 v[114:117], v[134:137], v[190:193], v[114:117]
	v_mfma_f32_16x16x32_bf16 v[106:109], v[142:145], v[190:193], v[106:109]
	v_mfma_f32_16x16x32_bf16 v[98:101], v[134:137], v[186:189], v[98:101]
	v_mfma_f32_16x16x32_bf16 v[90:93], v[142:145], v[186:189], v[90:93]
	v_mfma_f32_16x16x32_bf16 v[82:85], v[134:137], v[182:185], v[82:85]
	v_mfma_f32_16x16x32_bf16 v[74:77], v[142:145], v[182:185], v[74:77]
	v_mfma_f32_16x16x32_bf16 v[70:73], v[134:137], v[178:181], v[70:73]
	v_mfma_f32_16x16x32_bf16 v[66:69], v[142:145], v[178:181], v[66:69]
	s_setprio 1
	s_barrier
	s_and_b64 vcc, exec, s[42:43]
	s_cbranch_vccnz .LBB0_1295
	ds_read_b128 v[174:177], v231 offset:49152
	ds_read_b128 v[190:193], v231 offset:50176
	ds_read_b128 v[170:173], v231 offset:51200
	ds_read_b128 v[186:189], v231 offset:52224
	ds_read_b128 v[166:169], v231 offset:53248
	ds_read_b128 v[182:185], v231 offset:54272
	ds_read_b128 v[162:165], v231 offset:55296
	ds_read_b128 v[178:181], v231 offset:56320
.LBB0_1295:
	s_add_u32 s58, s52, 0x40000
	s_addc_u32 s59, s53, 0
	s_add_u32 s56, s56, 0x220000
	s_addc_u32 s57, s57, 0
	s_mov_b32 m0, s16
	s_add_u32 s52, s52, 0x44000
	global_load_lds_dwordx4 v194, s[58:59]
	s_mov_b32 m0, s17
	s_addc_u32 s53, s53, 0
	global_load_lds_dwordx4 v196, s[58:59]
	s_mov_b32 m0, s55
	s_and_b64 vcc, exec, s[42:43]
	global_load_lds_dwordx4 v194, s[52:53]
	s_mov_b32 m0, s60
	s_nop 0
	global_load_lds_dwordx4 v196, s[52:53]
	s_mov_b64 s[100:101], s[56:57]
	s_waitcnt vmcnt(6)
	s_waitcnt lgkmcnt(0)
	s_barrier
	s_cbranch_vccnz .LBB0_1288
	s_setprio 0
	s_waitcnt lgkmcnt(0)
	v_mfma_f32_16x16x32_bf16 v[62:65], v[146:149], v[174:177], v[62:65]
	v_mfma_f32_16x16x32_bf16 v[58:61], v[154:157], v[174:177], v[58:61]
	v_mfma_f32_16x16x32_bf16 v[46:49], v[146:149], v[170:173], v[46:49]
	v_mfma_f32_16x16x32_bf16 v[42:45], v[154:157], v[170:173], v[42:45]
	v_mfma_f32_16x16x32_bf16 v[30:33], v[146:149], v[166:169], v[30:33]
	v_mfma_f32_16x16x32_bf16 v[26:29], v[154:157], v[166:169], v[26:29]
	v_mfma_f32_16x16x32_bf16 v[14:17], v[146:149], v[162:165], v[14:17]
	v_mfma_f32_16x16x32_bf16 v[10:13], v[154:157], v[162:165], v[10:13]
	v_mfma_f32_16x16x32_bf16 v[62:65], v[150:153], v[190:193], v[62:65]
	v_mfma_f32_16x16x32_bf16 v[58:61], v[158:161], v[190:193], v[58:61]
	v_mfma_f32_16x16x32_bf16 v[46:49], v[150:153], v[186:189], v[46:49]
	v_mfma_f32_16x16x32_bf16 v[42:45], v[158:161], v[186:189], v[42:45]
	v_mfma_f32_16x16x32_bf16 v[30:33], v[150:153], v[182:185], v[30:33]
	v_mfma_f32_16x16x32_bf16 v[26:29], v[158:161], v[182:185], v[26:29]
	v_mfma_f32_16x16x32_bf16 v[14:17], v[150:153], v[178:181], v[14:17]
	v_mfma_f32_16x16x32_bf16 v[10:13], v[158:161], v[178:181], v[10:13]
	v_mfma_f32_16x16x32_bf16 v[54:57], v[130:133], v[174:177], v[54:57]
	v_mfma_f32_16x16x32_bf16 v[50:53], v[138:141], v[174:177], v[50:53]
	v_mfma_f32_16x16x32_bf16 v[38:41], v[130:133], v[170:173], v[38:41]
	v_mfma_f32_16x16x32_bf16 v[34:37], v[138:141], v[170:173], v[34:37]
	v_mfma_f32_16x16x32_bf16 v[22:25], v[130:133], v[166:169], v[22:25]
	v_mfma_f32_16x16x32_bf16 v[18:21], v[138:141], v[166:169], v[18:21]
	v_mfma_f32_16x16x32_bf16 v[6:9], v[130:133], v[162:165], v[6:9]
	v_mfma_f32_16x16x32_bf16 v[2:5], v[138:141], v[162:165], v[2:5]
	v_mfma_f32_16x16x32_bf16 v[54:57], v[134:137], v[190:193], v[54:57]
	v_mfma_f32_16x16x32_bf16 v[50:53], v[142:145], v[190:193], v[50:53]
	v_mfma_f32_16x16x32_bf16 v[38:41], v[134:137], v[186:189], v[38:41]
	v_mfma_f32_16x16x32_bf16 v[34:37], v[142:145], v[186:189], v[34:37]
	v_mfma_f32_16x16x32_bf16 v[22:25], v[134:137], v[182:185], v[22:25]
	v_mfma_f32_16x16x32_bf16 v[18:21], v[142:145], v[182:185], v[18:21]
	v_mfma_f32_16x16x32_bf16 v[6:9], v[134:137], v[178:181], v[6:9]
	v_mfma_f32_16x16x32_bf16 v[2:5], v[142:145], v[178:181], v[2:5]
	s_setprio 1
	s_branch .LBB0_1288

.LBB0_1612:
	s_mov_b32 m0, s54
	s_nop 0
	global_load_lds_dwordx4 v194, s[100:101]
	s_mov_b32 m0, s55
	s_nop 0
	global_load_lds_dwordx4 v196, s[100:101]
	v_add_u32_e32 v1, 0x10000, v232
	ds_read_b128 v[146:149], v1
	ds_read_b128 v[150:153], v1 offset:1024
	ds_read_b128 v[154:157], v1 offset:2048
	ds_read_b128 v[158:161], v1 offset:3072
	v_add_u32_e32 v1, 0x14000, v232
	ds_read_b128 v[130:133], v1
	ds_read_b128 v[134:137], v1 offset:1024
	ds_read_b128 v[138:141], v1 offset:2048
	ds_read_b128 v[142:145], v1 offset:3072
	v_lshl_add_u64 v[236:237], v[226:227], 0, s[48:49]
	s_add_i32 m0, s9, 0xc000
	s_waitcnt lgkmcnt(0)
	ds_read_b128 v[174:177], v233
	ds_read_b128 v[190:193], v233 offset:1024
	ds_read_b128 v[170:173], v233 offset:2048
	ds_read_b128 v[186:189], v233 offset:3072
	ds_read_b128 v[166:169], v233 offset:4096
	ds_read_b128 v[182:185], v233 offset:5120
	ds_read_b128 v[162:165], v233 offset:6144
	ds_read_b128 v[178:181], v233 offset:7168
	global_load_lds_dwordx4 v[236:237], off
	v_lshl_add_u64 v[236:237], v[228:229], 0, s[48:49]
	s_add_i32 m0, s9, 0xe000
	s_nop 0
	global_load_lds_dwordx4 v[236:237], off
	s_waitcnt vmcnt(8)
	s_waitcnt lgkmcnt(0)
	s_barrier
	s_setprio 0
	s_waitcnt lgkmcnt(0)
	v_mfma_f32_16x16x32_bf16 v[126:129], v[146:149], v[174:177], v[126:129]
	v_mfma_f32_16x16x32_bf16 v[122:125], v[154:157], v[174:177], v[122:125]
	v_mfma_f32_16x16x32_bf16 v[118:121], v[146:149], v[170:173], v[118:121]
	v_mfma_f32_16x16x32_bf16 v[110:113], v[154:157], v[170:173], v[110:113]
	v_mfma_f32_16x16x32_bf16 v[102:105], v[146:149], v[166:169], v[102:105]
	v_mfma_f32_16x16x32_bf16 v[94:97], v[154:157], v[166:169], v[94:97]
	v_mfma_f32_16x16x32_bf16 v[86:89], v[146:149], v[162:165], v[86:89]
	v_mfma_f32_16x16x32_bf16 v[78:81], v[154:157], v[162:165], v[78:81]
	v_mfma_f32_16x16x32_bf16 v[126:129], v[150:153], v[190:193], v[126:129]
	v_mfma_f32_16x16x32_bf16 v[122:125], v[158:161], v[190:193], v[122:125]
	v_mfma_f32_16x16x32_bf16 v[118:121], v[150:153], v[186:189], v[118:121]
	v_mfma_f32_16x16x32_bf16 v[110:113], v[158:161], v[186:189], v[110:113]
	v_mfma_f32_16x16x32_bf16 v[102:105], v[150:153], v[182:185], v[102:105]
	v_mfma_f32_16x16x32_bf16 v[94:97], v[158:161], v[182:185], v[94:97]
	v_mfma_f32_16x16x32_bf16 v[86:89], v[150:153], v[178:181], v[86:89]
	v_mfma_f32_16x16x32_bf16 v[78:81], v[158:161], v[178:181], v[78:81]
	v_mfma_f32_16x16x32_bf16 v[114:117], v[130:133], v[174:177], v[114:117]
	v_mfma_f32_16x16x32_bf16 v[106:109], v[138:141], v[174:177], v[106:109]
	v_mfma_f32_16x16x32_bf16 v[98:101], v[130:133], v[170:173], v[98:101]
	v_mfma_f32_16x16x32_bf16 v[90:93], v[138:141], v[170:173], v[90:93]
	v_mfma_f32_16x16x32_bf16 v[82:85], v[130:133], v[166:169], v[82:85]
	v_mfma_f32_16x16x32_bf16 v[74:77], v[138:141], v[166:169], v[74:77]
	v_mfma_f32_16x16x32_bf16 v[70:73], v[130:133], v[162:165], v[70:73]
	v_mfma_f32_16x16x32_bf16 v[66:69], v[138:141], v[162:165], v[66:69]
	v_mfma_f32_16x16x32_bf16 v[114:117], v[134:137], v[190:193], v[114:117]
	v_mfma_f32_16x16x32_bf16 v[106:109], v[142:145], v[190:193], v[106:109]
	v_mfma_f32_16x16x32_bf16 v[98:101], v[134:137], v[186:189], v[98:101]
	v_mfma_f32_16x16x32_bf16 v[90:93], v[142:145], v[186:189], v[90:93]
	v_mfma_f32_16x16x32_bf16 v[82:85], v[134:137], v[182:185], v[82:85]
	v_mfma_f32_16x16x32_bf16 v[74:77], v[142:145], v[182:185], v[74:77]
	v_mfma_f32_16x16x32_bf16 v[70:73], v[134:137], v[178:181], v[70:73]
	v_mfma_f32_16x16x32_bf16 v[66:69], v[142:145], v[178:181], v[66:69]
	s_setprio 1
	s_barrier
	v_cndmask_b32_e64 v1, 0, 1, s[40:41]
	v_cmp_ne_u32_e64 s[42:43], 1, v1
	s_andn2_b64 vcc, exec, s[40:41]
	s_cbranch_vccnz .LBB0_1614
	ds_read_b128 v[174:177], v233 offset:16384
	ds_read_b128 v[190:193], v233 offset:17408
	ds_read_b128 v[170:173], v233 offset:18432
	ds_read_b128 v[186:189], v233 offset:19456
	ds_read_b128 v[166:169], v233 offset:20480
	ds_read_b128 v[182:185], v233 offset:21504
	ds_read_b128 v[162:165], v233 offset:22528
	ds_read_b128 v[178:181], v233 offset:23552
.LBB0_1614:
	s_add_u32 s50, s46, s48
	s_addc_u32 s51, s47, s49
	s_add_u32 s52, s50, 0x440000
	s_addc_u32 s53, s51, 0
	s_cmp_eq_u32 s48, 0x3fc0000
	s_cselect_b64 s[56:57], -1, 0
	s_and_b64 s[50:51], s[56:57], exec
	s_cselect_b32 s51, s31, s61
	s_cselect_b32 s50, s35, s60
	s_mov_b32 m0, s10
	s_cselect_b32 s53, s19, s53
	s_cselect_b32 s52, s20, s52
	s_add_u32 s68, s50, 0x4000
	global_load_lds_dwordx4 v194, s[50:51]
	s_mov_b32 m0, s11
	s_addc_u32 s69, s51, 0
	global_load_lds_dwordx4 v196, s[50:51]
	s_mov_b32 m0, s12
	s_and_b64 vcc, exec, s[42:43]
	global_load_lds_dwordx4 v194, s[68:69]
	s_mov_b32 m0, s13
	s_nop 0
	global_load_lds_dwordx4 v196, s[68:69]
	s_mov_b64 s[98:99], s[52:53]
	s_waitcnt vmcnt(6)
	s_waitcnt lgkmcnt(0)
	s_barrier
	s_cbranch_vccnz .LBB0_1616
	s_setprio 0
	s_waitcnt lgkmcnt(0)
	v_mfma_f32_16x16x32_bf16 v[62:65], v[146:149], v[174:177], v[62:65]
	v_mfma_f32_16x16x32_bf16 v[58:61], v[154:157], v[174:177], v[58:61]
	v_mfma_f32_16x16x32_bf16 v[46:49], v[146:149], v[170:173], v[46:49]
	v_mfma_f32_16x16x32_bf16 v[42:45], v[154:157], v[170:173], v[42:45]
	v_mfma_f32_16x16x32_bf16 v[30:33], v[146:149], v[166:169], v[30:33]
	v_mfma_f32_16x16x32_bf16 v[26:29], v[154:157], v[166:169], v[26:29]
	v_mfma_f32_16x16x32_bf16 v[14:17], v[146:149], v[162:165], v[14:17]
	v_mfma_f32_16x16x32_bf16 v[10:13], v[154:157], v[162:165], v[10:13]
	v_mfma_f32_16x16x32_bf16 v[62:65], v[150:153], v[190:193], v[62:65]
	v_mfma_f32_16x16x32_bf16 v[58:61], v[158:161], v[190:193], v[58:61]
	v_mfma_f32_16x16x32_bf16 v[46:49], v[150:153], v[186:189], v[46:49]
	v_mfma_f32_16x16x32_bf16 v[42:45], v[158:161], v[186:189], v[42:45]
	v_mfma_f32_16x16x32_bf16 v[30:33], v[150:153], v[182:185], v[30:33]
	v_mfma_f32_16x16x32_bf16 v[26:29], v[158:161], v[182:185], v[26:29]
	v_mfma_f32_16x16x32_bf16 v[14:17], v[150:153], v[178:181], v[14:17]
	v_mfma_f32_16x16x32_bf16 v[10:13], v[158:161], v[178:181], v[10:13]
	v_mfma_f32_16x16x32_bf16 v[54:57], v[130:133], v[174:177], v[54:57]
	v_mfma_f32_16x16x32_bf16 v[50:53], v[138:141], v[174:177], v[50:53]
	v_mfma_f32_16x16x32_bf16 v[38:41], v[130:133], v[170:173], v[38:41]
	v_mfma_f32_16x16x32_bf16 v[34:37], v[138:141], v[170:173], v[34:37]
	v_mfma_f32_16x16x32_bf16 v[22:25], v[130:133], v[166:169], v[22:25]
	v_mfma_f32_16x16x32_bf16 v[18:21], v[138:141], v[166:169], v[18:21]
	v_mfma_f32_16x16x32_bf16 v[6:9], v[130:133], v[162:165], v[6:9]
	v_mfma_f32_16x16x32_bf16 v[2:5], v[138:141], v[162:165], v[2:5]
	v_mfma_f32_16x16x32_bf16 v[54:57], v[134:137], v[190:193], v[54:57]
	v_mfma_f32_16x16x32_bf16 v[50:53], v[142:145], v[190:193], v[50:53]
	v_mfma_f32_16x16x32_bf16 v[38:41], v[134:137], v[186:189], v[38:41]
	v_mfma_f32_16x16x32_bf16 v[34:37], v[142:145], v[186:189], v[34:37]
	v_mfma_f32_16x16x32_bf16 v[22:25], v[134:137], v[182:185], v[22:25]
	v_mfma_f32_16x16x32_bf16 v[18:21], v[142:145], v[182:185], v[18:21]
	v_mfma_f32_16x16x32_bf16 v[6:9], v[134:137], v[178:181], v[6:9]
	v_mfma_f32_16x16x32_bf16 v[2:5], v[142:145], v[178:181], v[2:5]
	s_setprio 1
.LBB0_1616:
	s_and_b64 vcc, s[38:39], s[56:57]
	v_cndmask_b32_e64 v131, v225, 0, vcc
	v_cndmask_b32_e32 v130, v224, v198, vcc
	v_lshl_add_u64 v[236:237], s[52:53], 0, v[130:131]
	s_barrier
	s_mov_b32 m0, s9
	s_nop 0
	global_load_lds_dwordx4 v194, s[98:99]
	s_mov_b32 m0, s14
	s_nop 0
	global_load_lds_dwordx4 v196, s[98:99]
	v_add_u32_e32 v1, 0x18000, v232
	ds_read_b128 v[146:149], v1
	ds_read_b128 v[150:153], v1 offset:1024
	ds_read_b128 v[154:157], v1 offset:2048
	ds_read_b128 v[158:161], v1 offset:3072
	v_add_u32_e32 v1, 0x1c000, v232
	ds_read_b128 v[130:133], v1
	ds_read_b128 v[134:137], v1 offset:1024
	ds_read_b128 v[138:141], v1 offset:2048
	ds_read_b128 v[142:145], v1 offset:3072
	s_mov_b32 m0, s15
	v_lshl_add_u64 v[238:239], v[236:237], 0, v[194:195]
	s_waitcnt lgkmcnt(0)
	ds_read_b128 v[174:177], v233 offset:32768
	ds_read_b128 v[190:193], v233 offset:33792
	ds_read_b128 v[170:173], v233 offset:34816
	ds_read_b128 v[186:189], v233 offset:35840
	ds_read_b128 v[166:169], v233 offset:36864
	ds_read_b128 v[182:185], v233 offset:37888
	ds_read_b128 v[162:165], v233 offset:38912
	ds_read_b128 v[178:181], v233 offset:39936
	global_load_lds_dwordx4 v[238:239], off
	v_lshl_add_u64 v[236:237], v[236:237], 0, v[196:197]
	s_mov_b32 m0, s16
	s_nop 0
	global_load_lds_dwordx4 v[236:237], off
	s_waitcnt vmcnt(8)
	s_waitcnt lgkmcnt(0)
	s_barrier
	s_setprio 0
	s_waitcnt lgkmcnt(0)
	v_mfma_f32_16x16x32_bf16 v[126:129], v[146:149], v[174:177], v[126:129]
	v_mfma_f32_16x16x32_bf16 v[122:125], v[154:157], v[174:177], v[122:125]
	v_mfma_f32_16x16x32_bf16 v[118:121], v[146:149], v[170:173], v[118:121]
	v_mfma_f32_16x16x32_bf16 v[110:113], v[154:157], v[170:173], v[110:113]
	v_mfma_f32_16x16x32_bf16 v[102:105], v[146:149], v[166:169], v[102:105]
	v_mfma_f32_16x16x32_bf16 v[94:97], v[154:157], v[166:169], v[94:97]
	v_mfma_f32_16x16x32_bf16 v[86:89], v[146:149], v[162:165], v[86:89]
	v_mfma_f32_16x16x32_bf16 v[78:81], v[154:157], v[162:165], v[78:81]
	v_mfma_f32_16x16x32_bf16 v[126:129], v[150:153], v[190:193], v[126:129]
	v_mfma_f32_16x16x32_bf16 v[122:125], v[158:161], v[190:193], v[122:125]
	v_mfma_f32_16x16x32_bf16 v[118:121], v[150:153], v[186:189], v[118:121]
	v_mfma_f32_16x16x32_bf16 v[110:113], v[158:161], v[186:189], v[110:113]
	v_mfma_f32_16x16x32_bf16 v[102:105], v[150:153], v[182:185], v[102:105]
	v_mfma_f32_16x16x32_bf16 v[94:97], v[158:161], v[182:185], v[94:97]
	v_mfma_f32_16x16x32_bf16 v[86:89], v[150:153], v[178:181], v[86:89]
	v_mfma_f32_16x16x32_bf16 v[78:81], v[158:161], v[178:181], v[78:81]
	v_mfma_f32_16x16x32_bf16 v[114:117], v[130:133], v[174:177], v[114:117]
	v_mfma_f32_16x16x32_bf16 v[106:109], v[138:141], v[174:177], v[106:109]
	v_mfma_f32_16x16x32_bf16 v[98:101], v[130:133], v[170:173], v[98:101]
	v_mfma_f32_16x16x32_bf16 v[90:93], v[138:141], v[170:173], v[90:93]
	v_mfma_f32_16x16x32_bf16 v[82:85], v[130:133], v[166:169], v[82:85]
	v_mfma_f32_16x16x32_bf16 v[74:77], v[138:141], v[166:169], v[74:77]
	v_mfma_f32_16x16x32_bf16 v[70:73], v[130:133], v[162:165], v[70:73]
	v_mfma_f32_16x16x32_bf16 v[66:69], v[138:141], v[162:165], v[66:69]
	v_mfma_f32_16x16x32_bf16 v[114:117], v[134:137], v[190:193], v[114:117]
	v_mfma_f32_16x16x32_bf16 v[106:109], v[142:145], v[190:193], v[106:109]
	v_mfma_f32_16x16x32_bf16 v[98:101], v[134:137], v[186:189], v[98:101]
	v_mfma_f32_16x16x32_bf16 v[90:93], v[142:145], v[186:189], v[90:93]
	v_mfma_f32_16x16x32_bf16 v[82:85], v[134:137], v[182:185], v[82:85]
	v_mfma_f32_16x16x32_bf16 v[74:77], v[142:145], v[182:185], v[74:77]
	v_mfma_f32_16x16x32_bf16 v[70:73], v[134:137], v[178:181], v[70:73]
	v_mfma_f32_16x16x32_bf16 v[66:69], v[142:145], v[178:181], v[66:69]
	s_setprio 1
	s_barrier
	s_and_b64 vcc, exec, s[42:43]
	s_cbranch_vccnz .LBB0_1618
	ds_read_b128 v[174:177], v233 offset:49152
	ds_read_b128 v[190:193], v233 offset:50176
	ds_read_b128 v[170:173], v233 offset:51200
	ds_read_b128 v[186:189], v233 offset:52224
	ds_read_b128 v[166:169], v233 offset:53248
	ds_read_b128 v[182:185], v233 offset:54272
	ds_read_b128 v[162:165], v233 offset:55296
	ds_read_b128 v[178:181], v233 offset:56320
.LBB0_1618:
	s_add_u32 s56, s50, 0x40000
	s_addc_u32 s57, s51, 0
	s_add_u32 s52, s52, 0x220000
	s_addc_u32 s53, s53, 0
	s_mov_b32 m0, s17
	s_add_u32 s50, s50, 0x44000
	global_load_lds_dwordx4 v194, s[56:57]
	s_mov_b32 m0, s29
	s_addc_u32 s51, s51, 0
	global_load_lds_dwordx4 v196, s[56:57]
	s_mov_b32 m0, s58
	s_and_b64 vcc, exec, s[42:43]
	global_load_lds_dwordx4 v194, s[50:51]
	s_mov_b32 m0, s59
	s_nop 0
	global_load_lds_dwordx4 v196, s[50:51]
	s_mov_b64 s[100:101], s[52:53]
	s_waitcnt vmcnt(6)
	s_waitcnt lgkmcnt(0)
	s_barrier
	s_cbranch_vccnz .LBB0_1611
	s_setprio 0
	s_waitcnt lgkmcnt(0)
	v_mfma_f32_16x16x32_bf16 v[62:65], v[146:149], v[174:177], v[62:65]
	v_mfma_f32_16x16x32_bf16 v[58:61], v[154:157], v[174:177], v[58:61]
	v_mfma_f32_16x16x32_bf16 v[46:49], v[146:149], v[170:173], v[46:49]
	v_mfma_f32_16x16x32_bf16 v[42:45], v[154:157], v[170:173], v[42:45]
	v_mfma_f32_16x16x32_bf16 v[30:33], v[146:149], v[166:169], v[30:33]
	v_mfma_f32_16x16x32_bf16 v[26:29], v[154:157], v[166:169], v[26:29]
	v_mfma_f32_16x16x32_bf16 v[14:17], v[146:149], v[162:165], v[14:17]
	v_mfma_f32_16x16x32_bf16 v[10:13], v[154:157], v[162:165], v[10:13]
	v_mfma_f32_16x16x32_bf16 v[62:65], v[150:153], v[190:193], v[62:65]
	v_mfma_f32_16x16x32_bf16 v[58:61], v[158:161], v[190:193], v[58:61]
	v_mfma_f32_16x16x32_bf16 v[46:49], v[150:153], v[186:189], v[46:49]
	v_mfma_f32_16x16x32_bf16 v[42:45], v[158:161], v[186:189], v[42:45]
	v_mfma_f32_16x16x32_bf16 v[30:33], v[150:153], v[182:185], v[30:33]
	v_mfma_f32_16x16x32_bf16 v[26:29], v[158:161], v[182:185], v[26:29]
	v_mfma_f32_16x16x32_bf16 v[14:17], v[150:153], v[178:181], v[14:17]
	v_mfma_f32_16x16x32_bf16 v[10:13], v[158:161], v[178:181], v[10:13]
	v_mfma_f32_16x16x32_bf16 v[54:57], v[130:133], v[174:177], v[54:57]
	v_mfma_f32_16x16x32_bf16 v[50:53], v[138:141], v[174:177], v[50:53]
	v_mfma_f32_16x16x32_bf16 v[38:41], v[130:133], v[170:173], v[38:41]
	v_mfma_f32_16x16x32_bf16 v[34:37], v[138:141], v[170:173], v[34:37]
	v_mfma_f32_16x16x32_bf16 v[22:25], v[130:133], v[166:169], v[22:25]
	v_mfma_f32_16x16x32_bf16 v[18:21], v[138:141], v[166:169], v[18:21]
	v_mfma_f32_16x16x32_bf16 v[6:9], v[130:133], v[162:165], v[6:9]
	v_mfma_f32_16x16x32_bf16 v[2:5], v[138:141], v[162:165], v[2:5]
	v_mfma_f32_16x16x32_bf16 v[54:57], v[134:137], v[190:193], v[54:57]
	v_mfma_f32_16x16x32_bf16 v[50:53], v[142:145], v[190:193], v[50:53]
	v_mfma_f32_16x16x32_bf16 v[38:41], v[134:137], v[186:189], v[38:41]
	v_mfma_f32_16x16x32_bf16 v[34:37], v[142:145], v[186:189], v[34:37]
	v_mfma_f32_16x16x32_bf16 v[22:25], v[134:137], v[182:185], v[22:25]
	v_mfma_f32_16x16x32_bf16 v[18:21], v[142:145], v[182:185], v[18:21]
	v_mfma_f32_16x16x32_bf16 v[6:9], v[134:137], v[178:181], v[6:9]
	v_mfma_f32_16x16x32_bf16 v[2:5], v[142:145], v[178:181], v[2:5]
	s_setprio 1
	s_branch .LBB0_1611
